# hoist rstd loads in G_UP epilogue; hand-written pipelined resid loops (DPP reduce, 2-row prefetch)
# speedup vs baseline: 1.0103x; 1.0103x over previous
; DI float bf_lo(unsigned u) { return __uint_as_float(u << 16); }
; DI float bf_hi(unsigned u) { return __uint_as_float(u & 0xffff0000u); }
; DI int otid() { int t = threadIdx.x; asm volatile("" : "+v"(t)); return t; }
; DI void phase_resid(const float* x_f32, bf16_t* xb, const bf16_t* y, const float* g_post, float* out_f32, float* rstd_out, bool write_xb) {
;   const int lane = otid() & 63;
;   const int gw = blockIdx.x * (NT / 64) + (otid() >> 6), nw = gridDim.x * (NT / 64);
;   for (int row = gw; row < T_TOK; row += nw) {
;     float xv[2][8];
; #pragma unroll
;     for (int j = 0; j < 2; ++j) {
;       const size_t off = (size_t)row * 1024 + j * 512 + lane * 8;
;       if (x_f32) {
;         const float4 a = *(const float4*)(x_f32 + off), c = *(const float4*)(x_f32 + off + 4);
;         xv[j][0] = a.x; xv[j][1] = a.y; xv[j][2] = a.z; xv[j][3] = a.w; xv[j][4] = c.x; xv[j][5] = c.y; xv[j][6] = c.z; xv[j][7] = c.w;
;       } else {
;         const uint4 u = *(const uint4*)(xb + off);
;         xv[j][0] = bf_lo(u.x); xv[j][1] = bf_hi(u.x); xv[j][2] = bf_lo(u.y); xv[j][3] = bf_hi(u.y);
;         xv[j][4] = bf_lo(u.z); xv[j][5] = bf_hi(u.z); xv[j][6] = bf_lo(u.w); xv[j][7] = bf_hi(u.w);
;       }
;     }
;     if (y) {
;       float yv[2][8];
;       float ss = 0.f;
; #pragma unroll
;       for (int j = 0; j < 2; ++j) {
;         const uint4 u = *(const uint4*)(y + (size_t)row * 1024 + j * 512 + lane * 8);
; DI void run_phase(const Params& p, int ph, char* smem) {
;     ...
;   const int l = (ph - 1) >> 3, q = (ph - 1) & 7;
;   switch (q) {
;     case 0: phase_gemm8<G_IN>(p, l, smem); break;
;     case 1: {
;       for (int t = blockIdx.x; t < 256 * 7; t += gridDim.x) {
;         if (t < 256 * 3) gemm_tile<G_UQ>(p, l, t, smem); else gemm_tile<G_UKV>(p, l, t - 256 * 3, smem);
;       }
;     } break;
;     case 2: phase_attn(p, l, smem); break;
;     case 3: phase_gemm8<G_OUT>(p, l, smem); break;
;     case 4: phase_resid(nullptr, act, mix, p.in[I_NMIXPOST] + l * 1024, nullptr, rstd, true); break;
;     case 5: phase_gemm8<G_UP>(p, l, smem); break;
;     case 6: phase_gemm8<G_DOWN>(p, l, smem); break;
;     case 7: if (l == 0) phase_resid(nullptr, act, mix, p.in[I_NMLPPOST] + l * 1024, nullptr, rstd, true);
;             else phase_resid(nullptr, act, mix, p.in[I_NMLPPOST] + l * 1024, p.out, nullptr, false);
.LBB0_10:
	s_cmp_lg_u32 s46, 0
	s_mov_b64 s[0:1], -1
	s_cbranch_scc0 .LBB0_581
	v_writelane_b32 v254, s46, 63
	s_nop 1
	v_writelane_b32 v255, s47, 0
	s_add_i32 s46, s46, -1
	s_ashr_i32 s0, s46, 3
	v_writelane_b32 v255, s0, 1
	s_nop 1
	v_writelane_b32 v255, s1, 2
	s_and_b32 s0, s46, 7
	v_writelane_b32 v255, s0, 3
	s_cmp_lt_i32 s0, 4
	s_mov_b64 s[0:1], -1
	s_cbranch_scc1 .LBB0_83
	v_readlane_b32 s0, v255, 3
	s_cmp_lt_i32 s0, 6
	s_mov_b64 s[0:1], -1
	s_cbranch_scc1 .LBB0_55
	v_readlane_b32 s0, v255, 3
	s_cmp_gt_i32 s0, 6
	s_mov_b64 s[0:1], -1
	s_cbranch_scc0 .LBB0_29
	v_readlane_b32 s0, v254, 63
	v_readlane_b32 s1, v255, 0
	s_cmp_gt_u32 s0, 8
	s_mov_b64 s[0:1], -1
	s_cbranch_scc0 .LBB0_21
	v_mov_b32_e32 v6, v228
	v_mov_b32_e32 v0, v228
	v_readlane_b32 s0, v251, 4
	v_ashrrev_i32_e32 v0, 6, v0
	s_nop 0
	v_add_u32_e32 v2, s0, v0
	s_mov_b32 s0, 0x10000
	v_cmp_gt_i32_e32 vcc, s0, v2
	s_and_saveexec_b64 s[0:1], vcc
	s_cbranch_execz .LBB0_20
	v_readlane_b32 s2, v255, 1
	v_readlane_b32 s3, v255, 2
	s_lshl_b32 s2, s2, 10
	s_ashr_i32 s3, s2, 31
	v_readlane_b32 s48, v253, 59
	s_lshl_b64 s[2:3], s[2:3], 2
	v_readlane_b32 s56, v254, 3
	v_readlane_b32 s57, v254, 4
	s_add_u32 s2, s56, s2
	v_lshlrev_b32_e32 v0, 5, v6
	s_addc_u32 s3, s57, s3
	v_and_b32_e32 v0, 0x7e0, v0
	v_cmp_lt_i32_e32 vcc, v234, v233
	s_waitcnt lgkmcnt(0)
	v_lshl_add_u64 v[4:5], s[2:3], 0, v[0:1]
	v_and_b32_e32 v10, 63, v6
	v_cndmask_b32_e32 v0, v232, v234, vcc
	v_cmp_lt_i32_e32 vcc, v235, v233
	v_readlane_b32 s2, v251, 2
	v_readlane_b32 s3, v251, 3
	v_cndmask_b32_e32 v3, v232, v235, vcc
	v_lshlrev_b32_e32 v28, 2, v3
	v_xor_b32_e32 v3, 8, v232
	v_cmp_lt_i32_e32 vcc, v3, v233
	v_readlane_b32 s62, v254, 9
	v_readlane_b32 s63, v254, 10
	v_cndmask_b32_e32 v3, v232, v3, vcc
	v_lshlrev_b32_e32 v29, 2, v3
	v_xor_b32_e32 v3, 4, v232
	v_cmp_lt_i32_e32 vcc, v3, v233
	v_readlane_b32 s49, v253, 60
	v_readlane_b32 s52, v253, 63
	v_cndmask_b32_e32 v3, v232, v3, vcc
	v_lshlrev_b32_e32 v30, 2, v3
	v_xor_b32_e32 v3, 2, v232
	v_cmp_lt_i32_e32 vcc, v3, v233
	v_readlane_b32 s54, v254, 1
	v_readlane_b32 s55, v254, 2
	v_cndmask_b32_e32 v3, v232, v3, vcc
	v_cmp_lt_i32_e32 vcc, v250, v233
	v_lshlrev_b32_e32 v31, 2, v3
	v_readlane_b32 s58, v254, 5
	v_cndmask_b32_e32 v3, v232, v250, vcc
	v_lshlrev_b32_e32 v32, 2, v3
	v_ashrrev_i32_e32 v3, 31, v2
	v_lshlrev_b64 v[8:9], 11, v[2:3]
	v_lshl_or_b32 v8, v10, 4, v8
	v_lshl_add_u64 v[6:7], s[2:3], 0, v[8:9]
	v_lshlrev_b64 v[8:9], 12, v[2:3]
	s_mov_b32 s62, 0x6dc9c883
	v_lshl_or_b32 v8, v10, 5, v8
	s_mov_b32 s49, 0xffff
	v_readlane_b32 s48, v254, 60
	s_mov_b32 s52, 0x3fb8aa3b
	s_movk_i32 s58, 0x204
	s_mov_b32 s55, 0x42b17218
	s_mov_b32 s54, 0xc2ce8ed0
	s_mov_b32 s63, 0x3fc45f30
	v_lshlrev_b32_e32 v0, 2, v0
	v_lshl_add_u64 v[8:9], s[84:85], 0, v[8:9]
	s_mov_b64 s[2:3], 0
	v_readlane_b32 s50, v253, 61
	v_readlane_b32 s51, v253, 62
	v_readlane_b32 s53, v254, 0
	v_readlane_b32 s59, v254, 6
	v_readlane_b32 s60, v254, 7
	v_readlane_b32 s61, v254, 8
	v_readfirstlane_b32 s2, v2
	global_load_dwordx4 v[100:103], v[4:5], off
	global_load_dwordx4 v[104:107], v[4:5], off offset:16
	global_load_dwordx4 v[108:111], v[4:5], off offset:2048
	global_load_dwordx4 v[112:115], v[4:5], off offset:2064
	s_add_u32 s4, s86, 0xaf0e000
	s_addc_u32 s5, s87, 0
	s_add_u32 s6, s86, 0x2f0e000
	s_addc_u32 s7, s87, 0
	v_and_b32_e32 v93, 63, v228
	v_lshlrev_b32_e32 v95, 5, v93
	v_lshlrev_b32_e32 v93, 4, v93
	v_readlane_b32 s98, v253, 43
	s_mov_b64 exec, -1
	s_lshl_b32 s3, s2, 11
	v_add_u32_e32 v91, s3, v93
	global_load_dwordx4 v[16:19], v91, s[4:5]
	global_load_dwordx4 v[20:23], v91, s[4:5] offset:1024
	global_load_dwordx4 v[24:27], v91, s[6:7]
	global_load_dwordx4 v[28:31], v91, s[6:7] offset:1024
	s_add_u32 s3, s2, s98
	s_min_u32 s3, s3, 0xffff
	s_lshl_b32 s3, s3, 11
	v_add_u32_e32 v91, s3, v93
	global_load_dwordx4 v[32:35], v91, s[4:5]
	global_load_dwordx4 v[36:39], v91, s[4:5] offset:1024
	global_load_dwordx4 v[40:43], v91, s[6:7]
	global_load_dwordx4 v[44:47], v91, s[6:7] offset:1024
	s_mov_b32 s99, 1
.Lresid_f_loop:
	s_cmp_eq_u32 s99, 1
	s_cbranch_scc1 .Lresid_f_0_wfirst
	s_waitcnt vmcnt(12)
	s_branch .Lresid_f_0_wdone
; DI float bf_lo(unsigned u) { return __uint_as_float(u << 16); }
; DI void phase_resid(const float* x_f32, bf16_t* xb, const bf16_t* y, const float* g_post, float* out_f32, float* rstd_out, bool write_xb) {
;     ...
;   for (int row = gw; row < T_TOK; row += nw) {
;     float xv[2][8];
; #pragma unroll
;     for (int j = 0; j < 2; ++j) {
;       const size_t off = (size_t)row * 1024 + j * 512 + lane * 8;
;       if (x_f32) {
;         const float4 a = *(const float4*)(x_f32 + off), c = *(const float4*)(x_f32 + off + 4);
;         xv[j][0] = a.x; xv[j][1] = a.y; xv[j][2] = a.z; xv[j][3] = a.w; xv[j][4] = c.x; xv[j][5] = c.y; xv[j][6] = c.z; xv[j][7] = c.w;
;       } else {
;         const uint4 u = *(const uint4*)(xb + off);
;         xv[j][0] = bf_lo(u.x); xv[j][1] = bf_hi(u.x); xv[j][2] = bf_lo(u.y); xv[j][3] = bf_hi(u.y);
;         xv[j][4] = bf_lo(u.z); xv[j][5] = bf_hi(u.z); xv[j][6] = bf_lo(u.w); xv[j][7] = bf_hi(u.w);
;       }
;     }
;     if (y) {
;       float yv[2][8];
;       float ss = 0.f;
; #pragma unroll
;       for (int j = 0; j < 2; ++j) {
;         const uint4 u = *(const uint4*)(y + (size_t)row * 1024 + j * 512 + lane * 8);
;         yv[j][0] = bf_lo(u.x); yv[j][1] = bf_hi(u.x); yv[j][2] = bf_lo(u.y); yv[j][3] = bf_hi(u.y);
;         yv[j][4] = bf_lo(u.z); yv[j][5] = bf_hi(u.z); yv[j][6] = bf_lo(u.w); yv[j][7] = bf_hi(u.w);
; #pragma unroll
;         for (int e = 0; e < 8; ++e) ss += yv[j][e] * yv[j][e];
;       }
;       ss = wave_sum(ss);
;       const float rs = frsq(ss * (1.f / 1024.f) + EPS);
; #pragma unroll
;       for (int j = 0; j < 2; ++j) {
;         const float4 g0 = *(const float4*)(g_post + j * 512 + lane * 8), g1 = *(const float4*)(g_post + j * 512 + lane * 8 + 4);
;         xv[j][0] += yv[j][0] * rs * g0.x; xv[j][1] += yv[j][1] * rs * g0.y; xv[j][2] += yv[j][2] * rs * g0.z; xv[j][3] += yv[j][3] * rs * g0.w;
;         xv[j][4] += yv[j][4] * rs * g1.x; xv[j][5] += yv[j][5] * rs * g1.y; xv[j][6] += yv[j][6] * rs * g1.z; xv[j][7] += yv[j][7] * rs * g1.w;
;       }
;     }
;     if (out_f32) {
; #pragma unroll
;       for (int j = 0; j < 2; ++j) {
;         const size_t off = (size_t)row * 1024 + j * 512 + lane * 8;
;         *(float4*)(out_f32 + off) = make_float4(xv[j][0], xv[j][1], xv[j][2], xv[j][3]);
;         *(float4*)(out_f32 + off + 4) = make_float4(xv[j][4], xv[j][5], xv[j][6], xv[j][7]);
;       }
.Lresid_f_0_wfirst:
	s_waitcnt vmcnt(4)
.Lresid_f_0_wdone:
	v_lshlrev_b32_e32 v48, 16, v16
	v_and_b32_e32 v49, 0xffff0000, v16
	v_lshlrev_b32_e32 v50, 16, v17
	v_and_b32_e32 v51, 0xffff0000, v17
	v_lshlrev_b32_e32 v52, 16, v18
	v_and_b32_e32 v53, 0xffff0000, v18
	v_lshlrev_b32_e32 v54, 16, v19
	v_and_b32_e32 v55, 0xffff0000, v19
	v_lshlrev_b32_e32 v56, 16, v20
	v_and_b32_e32 v57, 0xffff0000, v20
	v_lshlrev_b32_e32 v58, 16, v21
	v_and_b32_e32 v59, 0xffff0000, v21
	v_lshlrev_b32_e32 v60, 16, v22
	v_and_b32_e32 v61, 0xffff0000, v22
	v_lshlrev_b32_e32 v62, 16, v23
	v_and_b32_e32 v63, 0xffff0000, v23
	v_lshlrev_b32_e32 v64, 16, v24
	v_and_b32_e32 v65, 0xffff0000, v24
	v_lshlrev_b32_e32 v66, 16, v25
	v_and_b32_e32 v67, 0xffff0000, v25
	v_lshlrev_b32_e32 v68, 16, v26
	v_and_b32_e32 v69, 0xffff0000, v26
	v_lshlrev_b32_e32 v70, 16, v27
	v_and_b32_e32 v71, 0xffff0000, v27
	v_lshlrev_b32_e32 v72, 16, v28
	v_and_b32_e32 v73, 0xffff0000, v28
	v_lshlrev_b32_e32 v74, 16, v29
	v_and_b32_e32 v75, 0xffff0000, v29
	v_lshlrev_b32_e32 v76, 16, v30
	v_and_b32_e32 v77, 0xffff0000, v30
	v_lshlrev_b32_e32 v78, 16, v31
	v_and_b32_e32 v79, 0xffff0000, v31
	s_lshl_b32 s3, s2, 11
	v_add_u32_e32 v90, s3, v93
	s_lshl_b32 s3, s2, 12
	v_add_u32_e32 v94, s3, v95
	s_add_u32 s3, s2, s98
	s_add_u32 s3, s3, s98
	s_min_u32 s3, s3, 0xffff
	s_lshl_b32 s3, s3, 11
	v_add_u32_e32 v91, s3, v93
	global_load_dwordx4 v[16:19], v91, s[4:5]
	global_load_dwordx4 v[20:23], v91, s[4:5] offset:1024
	global_load_dwordx4 v[24:27], v91, s[6:7]
	global_load_dwordx4 v[28:31], v91, s[6:7] offset:1024
	v_mul_f32_e32 v80, v48, v48
	v_mul_f32_e32 v81, v49, v49
	v_fmac_f32_e32 v80, v50, v50
	v_fmac_f32_e32 v81, v51, v51
	v_fmac_f32_e32 v80, v52, v52
	v_fmac_f32_e32 v81, v53, v53
	v_fmac_f32_e32 v80, v54, v54
	v_fmac_f32_e32 v81, v55, v55
	v_fmac_f32_e32 v80, v56, v56
	v_fmac_f32_e32 v81, v57, v57
	v_fmac_f32_e32 v80, v58, v58
	v_fmac_f32_e32 v81, v59, v59
	v_fmac_f32_e32 v80, v60, v60
	v_fmac_f32_e32 v81, v61, v61
	v_fmac_f32_e32 v80, v62, v62
	v_fmac_f32_e32 v81, v63, v63
	v_add_f32_e32 v80, v80, v81
	s_nop 1
	v_add_f32_dpp v80, v80, v80 quad_perm:[1,0,3,2] row_mask:0xf bank_mask:0xf
	s_nop 1
	v_add_f32_dpp v80, v80, v80 quad_perm:[2,3,0,1] row_mask:0xf bank_mask:0xf
	s_nop 1
	v_add_f32_dpp v80, v80, v80 row_half_mirror row_mask:0xf bank_mask:0xf
	s_nop 1
	v_add_f32_dpp v80, v80, v80 row_mirror row_mask:0xf bank_mask:0xf
	s_nop 1
	v_add_f32_dpp v80, v80, v80 row_bcast:15 row_mask:0xa bank_mask:0xf
	s_nop 1
	v_add_f32_dpp v80, v80, v80 row_bcast:31 row_mask:0xc bank_mask:0xf
	s_nop 1
	v_readlane_b32 s3, v80, 63
	s_nop 1
	v_mov_b32_e32 v80, s3
	v_fmamk_f32 v80, v80, 0x3a800000, v229
	v_rsq_f32_e32 v80, v80
	s_nop 0
	v_mul_f32_e32 v48, v80, v48
	v_mul_f32_e32 v49, v80, v49
	v_mul_f32_e32 v50, v80, v50
	v_mul_f32_e32 v51, v80, v51
	v_mul_f32_e32 v52, v80, v52
	v_mul_f32_e32 v53, v80, v53
	v_mul_f32_e32 v54, v80, v54
	v_mul_f32_e32 v55, v80, v55
	v_mul_f32_e32 v56, v80, v56
	v_mul_f32_e32 v57, v80, v57
	v_mul_f32_e32 v58, v80, v58
	v_mul_f32_e32 v59, v80, v59
	v_mul_f32_e32 v60, v80, v60
	v_mul_f32_e32 v61, v80, v61
	v_mul_f32_e32 v62, v80, v62
	v_mul_f32_e32 v63, v80, v63
	v_fmac_f32_e32 v64, v100, v48
	v_fmac_f32_e32 v65, v101, v49
	v_fmac_f32_e32 v66, v102, v50
	v_fmac_f32_e32 v67, v103, v51
	v_fmac_f32_e32 v68, v104, v52
	v_fmac_f32_e32 v69, v105, v53
	v_fmac_f32_e32 v70, v106, v54
	v_fmac_f32_e32 v71, v107, v55
	v_fmac_f32_e32 v72, v108, v56
	v_fmac_f32_e32 v73, v109, v57
	v_fmac_f32_e32 v74, v110, v58
	v_fmac_f32_e32 v75, v111, v59
	v_fmac_f32_e32 v76, v112, v60
	v_fmac_f32_e32 v77, v113, v61
	v_fmac_f32_e32 v78, v114, v62
	v_fmac_f32_e32 v79, v115, v63
	global_store_dwordx4 v94, v[64:67], s[84:85]
	global_store_dwordx4 v94, v[68:71], s[84:85] offset:16
	global_store_dwordx4 v94, v[72:75], s[84:85] offset:2048
	global_store_dwordx4 v94, v[76:79], s[84:85] offset:2064
	s_add_u32 s2, s2, s98
	s_cmp_gt_u32 s2, 0xffff
	s_cbranch_scc1 .Lresid_f_done
	s_cmp_eq_u32 s99, 1
	s_cbranch_scc1 .Lresid_f_1_wfirst
	s_waitcnt vmcnt(12)
	s_branch .Lresid_f_1_wdone

; DI float bf_lo(unsigned u) { return __uint_as_float(u << 16); }
; DI void phase_resid(const float* x_f32, bf16_t* xb, const bf16_t* y, const float* g_post, float* out_f32, float* rstd_out, bool write_xb) {
;     ...
;   for (int row = gw; row < T_TOK; row += nw) {
;     float xv[2][8];
; #pragma unroll
;     for (int j = 0; j < 2; ++j) {
;       const size_t off = (size_t)row * 1024 + j * 512 + lane * 8;
;       if (x_f32) {
;         const float4 a = *(const float4*)(x_f32 + off), c = *(const float4*)(x_f32 + off + 4);
;         xv[j][0] = a.x; xv[j][1] = a.y; xv[j][2] = a.z; xv[j][3] = a.w; xv[j][4] = c.x; xv[j][5] = c.y; xv[j][6] = c.z; xv[j][7] = c.w;
;       } else {
;         const uint4 u = *(const uint4*)(xb + off);
;         xv[j][0] = bf_lo(u.x); xv[j][1] = bf_hi(u.x); xv[j][2] = bf_lo(u.y); xv[j][3] = bf_hi(u.y);
;         xv[j][4] = bf_lo(u.z); xv[j][5] = bf_hi(u.z); xv[j][6] = bf_lo(u.w); xv[j][7] = bf_hi(u.w);
;       }
;     }
;     if (y) {
;       float yv[2][8];
;       float ss = 0.f;
; #pragma unroll
;       for (int j = 0; j < 2; ++j) {
;         const uint4 u = *(const uint4*)(y + (size_t)row * 1024 + j * 512 + lane * 8);
;         yv[j][0] = bf_lo(u.x); yv[j][1] = bf_hi(u.x); yv[j][2] = bf_lo(u.y); yv[j][3] = bf_hi(u.y);
;         yv[j][4] = bf_lo(u.z); yv[j][5] = bf_hi(u.z); yv[j][6] = bf_lo(u.w); yv[j][7] = bf_hi(u.w);
; #pragma unroll
;         for (int e = 0; e < 8; ++e) ss += yv[j][e] * yv[j][e];
;       }
;       ss = wave_sum(ss);
;       const float rs = frsq(ss * (1.f / 1024.f) + EPS);
; #pragma unroll
;       for (int j = 0; j < 2; ++j) {
;         const float4 g0 = *(const float4*)(g_post + j * 512 + lane * 8), g1 = *(const float4*)(g_post + j * 512 + lane * 8 + 4);
;         xv[j][0] += yv[j][0] * rs * g0.x; xv[j][1] += yv[j][1] * rs * g0.y; xv[j][2] += yv[j][2] * rs * g0.z; xv[j][3] += yv[j][3] * rs * g0.w;
;         xv[j][4] += yv[j][4] * rs * g1.x; xv[j][5] += yv[j][5] * rs * g1.y; xv[j][6] += yv[j][6] * rs * g1.z; xv[j][7] += yv[j][7] * rs * g1.w;
;       }
;     }
;     if (out_f32) {
; #pragma unroll
;       for (int j = 0; j < 2; ++j) {
;         const size_t off = (size_t)row * 1024 + j * 512 + lane * 8;
;         *(float4*)(out_f32 + off) = make_float4(xv[j][0], xv[j][1], xv[j][2], xv[j][3]);
;         *(float4*)(out_f32 + off + 4) = make_float4(xv[j][4], xv[j][5], xv[j][6], xv[j][7]);
;       }
.Lresid_f_1_wdone:
	v_lshlrev_b32_e32 v48, 16, v32
	v_and_b32_e32 v49, 0xffff0000, v32
	v_lshlrev_b32_e32 v50, 16, v33
	v_and_b32_e32 v51, 0xffff0000, v33
	v_lshlrev_b32_e32 v52, 16, v34
	v_and_b32_e32 v53, 0xffff0000, v34
	v_lshlrev_b32_e32 v54, 16, v35
	v_and_b32_e32 v55, 0xffff0000, v35
	v_lshlrev_b32_e32 v56, 16, v36
	v_and_b32_e32 v57, 0xffff0000, v36
	v_lshlrev_b32_e32 v58, 16, v37
	v_and_b32_e32 v59, 0xffff0000, v37
	v_lshlrev_b32_e32 v60, 16, v38
	v_and_b32_e32 v61, 0xffff0000, v38
	v_lshlrev_b32_e32 v62, 16, v39
	v_and_b32_e32 v63, 0xffff0000, v39
	v_lshlrev_b32_e32 v64, 16, v40
	v_and_b32_e32 v65, 0xffff0000, v40
	v_lshlrev_b32_e32 v66, 16, v41
	v_and_b32_e32 v67, 0xffff0000, v41
	v_lshlrev_b32_e32 v68, 16, v42
	v_and_b32_e32 v69, 0xffff0000, v42
	v_lshlrev_b32_e32 v70, 16, v43
	v_and_b32_e32 v71, 0xffff0000, v43
	v_lshlrev_b32_e32 v72, 16, v44
	v_and_b32_e32 v73, 0xffff0000, v44
	v_lshlrev_b32_e32 v74, 16, v45
	v_and_b32_e32 v75, 0xffff0000, v45
	v_lshlrev_b32_e32 v76, 16, v46
	v_and_b32_e32 v77, 0xffff0000, v46
	v_lshlrev_b32_e32 v78, 16, v47
	v_and_b32_e32 v79, 0xffff0000, v47
	s_lshl_b32 s3, s2, 11
	v_add_u32_e32 v90, s3, v93
	s_lshl_b32 s3, s2, 12
	v_add_u32_e32 v94, s3, v95
	s_add_u32 s3, s2, s98
	s_add_u32 s3, s3, s98
	s_min_u32 s3, s3, 0xffff
	s_lshl_b32 s3, s3, 11
	v_add_u32_e32 v91, s3, v93
	global_load_dwordx4 v[32:35], v91, s[4:5]
	global_load_dwordx4 v[36:39], v91, s[4:5] offset:1024
	global_load_dwordx4 v[40:43], v91, s[6:7]
	global_load_dwordx4 v[44:47], v91, s[6:7] offset:1024
	v_mul_f32_e32 v80, v48, v48
	v_mul_f32_e32 v81, v49, v49
	v_fmac_f32_e32 v80, v50, v50
	v_fmac_f32_e32 v81, v51, v51
	v_fmac_f32_e32 v80, v52, v52
	v_fmac_f32_e32 v81, v53, v53
	v_fmac_f32_e32 v80, v54, v54
	v_fmac_f32_e32 v81, v55, v55
	v_fmac_f32_e32 v80, v56, v56
	v_fmac_f32_e32 v81, v57, v57
	v_fmac_f32_e32 v80, v58, v58
	v_fmac_f32_e32 v81, v59, v59
	v_fmac_f32_e32 v80, v60, v60
	v_fmac_f32_e32 v81, v61, v61
	v_fmac_f32_e32 v80, v62, v62
	v_fmac_f32_e32 v81, v63, v63
	v_add_f32_e32 v80, v80, v81
	s_nop 1
	v_add_f32_dpp v80, v80, v80 quad_perm:[1,0,3,2] row_mask:0xf bank_mask:0xf
	s_nop 1
	v_add_f32_dpp v80, v80, v80 quad_perm:[2,3,0,1] row_mask:0xf bank_mask:0xf
	s_nop 1
	v_add_f32_dpp v80, v80, v80 row_half_mirror row_mask:0xf bank_mask:0xf
	s_nop 1
	v_add_f32_dpp v80, v80, v80 row_mirror row_mask:0xf bank_mask:0xf
	s_nop 1
	v_add_f32_dpp v80, v80, v80 row_bcast:15 row_mask:0xa bank_mask:0xf
	s_nop 1
	v_add_f32_dpp v80, v80, v80 row_bcast:31 row_mask:0xc bank_mask:0xf
	s_nop 1
	v_readlane_b32 s3, v80, 63
	s_nop 1
	v_mov_b32_e32 v80, s3
	v_fmamk_f32 v80, v80, 0x3a800000, v229
	v_rsq_f32_e32 v80, v80
	s_nop 0
	v_mul_f32_e32 v48, v80, v48
	v_mul_f32_e32 v49, v80, v49
	v_mul_f32_e32 v50, v80, v50
	v_mul_f32_e32 v51, v80, v51
	v_mul_f32_e32 v52, v80, v52
	v_mul_f32_e32 v53, v80, v53
	v_mul_f32_e32 v54, v80, v54
	v_mul_f32_e32 v55, v80, v55
	v_mul_f32_e32 v56, v80, v56
	v_mul_f32_e32 v57, v80, v57
	v_mul_f32_e32 v58, v80, v58
	v_mul_f32_e32 v59, v80, v59
	v_mul_f32_e32 v60, v80, v60
	v_mul_f32_e32 v61, v80, v61
	v_mul_f32_e32 v62, v80, v62
	v_mul_f32_e32 v63, v80, v63
	v_fmac_f32_e32 v64, v100, v48
	v_fmac_f32_e32 v65, v101, v49
	v_fmac_f32_e32 v66, v102, v50
	v_fmac_f32_e32 v67, v103, v51
	v_fmac_f32_e32 v68, v104, v52
	v_fmac_f32_e32 v69, v105, v53
	v_fmac_f32_e32 v70, v106, v54
	v_fmac_f32_e32 v71, v107, v55
	v_fmac_f32_e32 v72, v108, v56
	v_fmac_f32_e32 v73, v109, v57
	v_fmac_f32_e32 v74, v110, v58
	v_fmac_f32_e32 v75, v111, v59
	v_fmac_f32_e32 v76, v112, v60
	v_fmac_f32_e32 v77, v113, v61
	v_fmac_f32_e32 v78, v114, v62
	v_fmac_f32_e32 v79, v115, v63
	global_store_dwordx4 v94, v[64:67], s[84:85]
	global_store_dwordx4 v94, v[68:71], s[84:85] offset:16
	global_store_dwordx4 v94, v[72:75], s[84:85] offset:2048
	global_store_dwordx4 v94, v[76:79], s[84:85] offset:2064
	s_add_u32 s2, s2, s98
	s_cmp_gt_u32 s2, 0xffff
	s_cbranch_scc1 .Lresid_f_done
	s_mov_b32 s99, 0
	s_branch .Lresid_f_loop
; DI float bf_lo(unsigned u) { return __uint_as_float(u << 16); }
; DI float bf_hi(unsigned u) { return __uint_as_float(u & 0xffff0000u); }
; DI int otid() { int t = threadIdx.x; asm volatile("" : "+v"(t)); return t; }
; DI void phase_resid(const float* x_f32, bf16_t* xb, const bf16_t* y, const float* g_post, float* out_f32, float* rstd_out, bool write_xb) {
;   const int lane = otid() & 63;
;   const int gw = blockIdx.x * (NT / 64) + (otid() >> 6), nw = gridDim.x * (NT / 64);
;   for (int row = gw; row < T_TOK; row += nw) {
;     float xv[2][8];
; #pragma unroll
;     for (int j = 0; j < 2; ++j) {
;       const size_t off = (size_t)row * 1024 + j * 512 + lane * 8;
;       if (x_f32) {
;         const float4 a = *(const float4*)(x_f32 + off), c = *(const float4*)(x_f32 + off + 4);
;         xv[j][0] = a.x; xv[j][1] = a.y; xv[j][2] = a.z; xv[j][3] = a.w; xv[j][4] = c.x; xv[j][5] = c.y; xv[j][6] = c.z; xv[j][7] = c.w;
;       } else {
;         const uint4 u = *(const uint4*)(xb + off);
;         xv[j][0] = bf_lo(u.x); xv[j][1] = bf_hi(u.x); xv[j][2] = bf_lo(u.y); xv[j][3] = bf_hi(u.y);
;         xv[j][4] = bf_lo(u.z); xv[j][5] = bf_hi(u.z); xv[j][6] = bf_lo(u.w); xv[j][7] = bf_hi(u.w);
;       }
;     }
;     if (y) {
;       float yv[2][8];
;       float ss = 0.f;
; #pragma unroll
;       for (int j = 0; j < 2; ++j) {
;         const uint4 u = *(const uint4*)(y + (size_t)row * 1024 + j * 512 + lane * 8);
.Lresid_f_done:
	s_waitcnt vmcnt(0)
.LBB0_20:
	s_or_b64 exec, exec, s[0:1]
	s_mov_b64 s[0:1], 0
.LBB0_21:
	s_andn2_b64 vcc, exec, s[0:1]
	s_cbranch_vccnz .LBB0_28
	v_mov_b32_e32 v0, v228
	v_mov_b32_e32 v2, v228
	v_readlane_b32 s0, v251, 4
	v_ashrrev_i32_e32 v2, 6, v2
	s_nop 0
	v_add_u32_e32 v2, s0, v2
	s_mov_b32 s0, 0x10000
	v_cmp_gt_i32_e32 vcc, s0, v2
	s_and_saveexec_b64 s[2:3], vcc
	s_cbranch_execz .LBB0_27
	s_waitcnt lgkmcnt(0)
	v_and_b32_e32 v15, 63, v0
	v_readlane_b32 s48, v253, 59
	v_lshlrev_b32_e32 v0, 5, v15
	v_readlane_b32 s56, v254, 3
	v_readlane_b32 s57, v254, 4
	v_cmp_lt_i32_e32 vcc, v234, v233
	v_readlane_b32 s62, v254, 9
	v_lshl_add_u64 v[4:5], s[56:57], 0, v[0:1]
	v_cndmask_b32_e32 v0, v232, v234, vcc
	v_cmp_lt_i32_e32 vcc, v235, v233
	v_readlane_b32 s63, v254, 10
	v_readlane_b32 s49, v253, 60
	v_cndmask_b32_e32 v3, v232, v235, vcc
	s_waitcnt lgkmcnt(0)
	v_lshlrev_b32_e32 v10, 2, v3
	v_xor_b32_e32 v3, 8, v232
	v_cmp_lt_i32_e32 vcc, v3, v233
	v_readlane_b32 s52, v253, 63
	v_readlane_b32 s54, v254, 1
	v_cndmask_b32_e32 v3, v232, v3, vcc
	v_lshlrev_b32_e32 v11, 2, v3
	v_xor_b32_e32 v3, 4, v232
	v_cmp_lt_i32_e32 vcc, v3, v233
	v_readlane_b32 s55, v254, 2
	v_readlane_b32 s58, v254, 5
	v_cndmask_b32_e32 v3, v232, v3, vcc
	v_lshlrev_b32_e32 v12, 2, v3
	v_xor_b32_e32 v3, 2, v232
	v_cmp_lt_i32_e32 vcc, v3, v233
	s_mov_b32 s62, 0x6dc9c883
	v_mov_b64_e32 v[6:7], 0x1b10e000
	v_cndmask_b32_e32 v3, v232, v3, vcc
	v_cmp_lt_i32_e32 vcc, v250, v233
	v_lshlrev_b32_e32 v13, 2, v3
	s_mov_b32 s52, 0x3fb8aa3b
	v_cndmask_b32_e32 v3, v232, v250, vcc
	v_lshlrev_b32_e32 v14, 2, v3
	v_ashrrev_i32_e32 v3, 31, v2
	v_lshlrev_b64 v[8:9], 11, v[2:3]
	s_movk_i32 s58, 0x204
	s_mov_b32 s55, 0x42b17218
	s_mov_b32 s54, 0xc2ce8ed0
	s_mov_b32 s49, 0xffff
	s_mov_b32 s63, 0x3fc45f30
	v_readlane_b32 s48, v254, 60
	v_cmp_eq_u32_e64 s[0:1], 0, v15
	v_lshlrev_b32_e32 v0, 2, v0
	v_lshl_add_u64 v[6:7], v[2:3], 2, v[6:7]
	v_lshl_or_b32 v8, v15, 4, v8
	s_mov_b64 s[4:5], 0
	v_readlane_b32 s50, v253, 61
	v_readlane_b32 s51, v253, 62
	v_readlane_b32 s53, v254, 0
	v_readlane_b32 s59, v254, 6
	v_readlane_b32 s60, v254, 7
	v_readlane_b32 s61, v254, 8
	v_readfirstlane_b32 s0, v2
	global_load_dwordx4 v[100:103], v[4:5], off
	global_load_dwordx4 v[104:107], v[4:5], off offset:16
	global_load_dwordx4 v[108:111], v[4:5], off offset:2048
	global_load_dwordx4 v[112:115], v[4:5], off offset:2064
	s_add_u32 s4, s86, 0xaf0e000
	s_addc_u32 s5, s87, 0
	s_add_u32 s6, s86, 0x2f0e000
	s_addc_u32 s7, s87, 0
	v_and_b32_e32 v93, 63, v228
	v_lshlrev_b32_e32 v95, 5, v93
	v_lshlrev_b32_e32 v93, 4, v93
	v_readlane_b32 s98, v253, 43
	s_mov_b64 exec, -1
	s_lshl_b32 s1, s0, 11
	v_add_u32_e32 v91, s1, v93
	global_load_dwordx4 v[16:19], v91, s[4:5]
	global_load_dwordx4 v[20:23], v91, s[4:5] offset:1024
	global_load_dwordx4 v[24:27], v91, s[6:7]
	global_load_dwordx4 v[28:31], v91, s[6:7] offset:1024
	s_add_u32 s1, s0, s98
	s_min_u32 s1, s1, 0xffff
	s_lshl_b32 s1, s1, 11
	v_add_u32_e32 v91, s1, v93
	global_load_dwordx4 v[32:35], v91, s[4:5]
	global_load_dwordx4 v[36:39], v91, s[4:5] offset:1024
	global_load_dwordx4 v[40:43], v91, s[6:7]
	global_load_dwordx4 v[44:47], v91, s[6:7] offset:1024
	s_mov_b32 s99, 1
.Lresid_a_loop:
	s_cmp_eq_u32 s99, 1
	s_cbranch_scc1 .Lresid_a_0_wfirst
	s_waitcnt vmcnt(10)
	s_branch .Lresid_a_0_wdone

; DI void phase_resid(const float* x_f32, bf16_t* xb, const bf16_t* y, const float* g_post, float* out_f32, float* rstd_out, bool write_xb) {
;     ...
;   for (int row = gw; row < T_TOK; row += nw) {
;     float xv[2][8];
; #pragma unroll
;     for (int j = 0; j < 2; ++j) {
;       const size_t off = (size_t)row * 1024 + j * 512 + lane * 8;
;       if (x_f32) {
;         const float4 a = *(const float4*)(x_f32 + off), c = *(const float4*)(x_f32 + off + 4);
;         xv[j][0] = a.x; xv[j][1] = a.y; xv[j][2] = a.z; xv[j][3] = a.w; xv[j][4] = c.x; xv[j][5] = c.y; xv[j][6] = c.z; xv[j][7] = c.w;
;       } else {
;         const uint4 u = *(const uint4*)(xb + off);
;         xv[j][0] = bf_lo(u.x); xv[j][1] = bf_hi(u.x); xv[j][2] = bf_lo(u.y); xv[j][3] = bf_hi(u.y);
;         xv[j][4] = bf_lo(u.z); xv[j][5] = bf_hi(u.z); xv[j][6] = bf_lo(u.w); xv[j][7] = bf_hi(u.w);
;       }
;     }
;     if (y) {
;       float yv[2][8];
;       float ss = 0.f;
; #pragma unroll
;       for (int j = 0; j < 2; ++j) {
;         const uint4 u = *(const uint4*)(y + (size_t)row * 1024 + j * 512 + lane * 8);
;         yv[j][0] = bf_lo(u.x); yv[j][1] = bf_hi(u.x); yv[j][2] = bf_lo(u.y); yv[j][3] = bf_hi(u.y);
;         yv[j][4] = bf_lo(u.z); yv[j][5] = bf_hi(u.z); yv[j][6] = bf_lo(u.w); yv[j][7] = bf_hi(u.w);
; #pragma unroll
;         for (int e = 0; e < 8; ++e) ss += yv[j][e] * yv[j][e];
;       }
;       ss = wave_sum(ss);
;       const float rs = frsq(ss * (1.f / 1024.f) + EPS);
; #pragma unroll
;       for (int j = 0; j < 2; ++j) {
;         const float4 g0 = *(const float4*)(g_post + j * 512 + lane * 8), g1 = *(const float4*)(g_post + j * 512 + lane * 8 + 4);
;         xv[j][0] += yv[j][0] * rs * g0.x; xv[j][1] += yv[j][1] * rs * g0.y; xv[j][2] += yv[j][2] * rs * g0.z; xv[j][3] += yv[j][3] * rs * g0.w;
;         xv[j][4] += yv[j][4] * rs * g1.x; xv[j][5] += yv[j][5] * rs * g1.y; xv[j][6] += yv[j][6] * rs * g1.z; xv[j][7] += yv[j][7] * rs * g1.w;
;       }
;     }
;     if (out_f32) {
; #pragma unroll
;       for (int j = 0; j < 2; ++j) {
;         const size_t off = (size_t)row * 1024 + j * 512 + lane * 8;
;         *(float4*)(out_f32 + off) = make_float4(xv[j][0], xv[j][1], xv[j][2], xv[j][3]);
;         *(float4*)(out_f32 + off + 4) = make_float4(xv[j][4], xv[j][5], xv[j][6], xv[j][7]);
;       }
;     }
;     if (write_xb) {
; #pragma unroll
;       for (int j = 0; j < 2; ++j) {
.Lresid_a_0_wdone:
	v_lshlrev_b32_e32 v48, 16, v16
	v_and_b32_e32 v49, 0xffff0000, v16
	v_lshlrev_b32_e32 v50, 16, v17
	v_and_b32_e32 v51, 0xffff0000, v17
	v_lshlrev_b32_e32 v52, 16, v18
	v_and_b32_e32 v53, 0xffff0000, v18
	v_lshlrev_b32_e32 v54, 16, v19
	v_and_b32_e32 v55, 0xffff0000, v19
	v_lshlrev_b32_e32 v56, 16, v20
	v_and_b32_e32 v57, 0xffff0000, v20
	v_lshlrev_b32_e32 v58, 16, v21
	v_and_b32_e32 v59, 0xffff0000, v21
	v_lshlrev_b32_e32 v60, 16, v22
	v_and_b32_e32 v61, 0xffff0000, v22
	v_lshlrev_b32_e32 v62, 16, v23
	v_and_b32_e32 v63, 0xffff0000, v23
	v_lshlrev_b32_e32 v64, 16, v24
	v_and_b32_e32 v65, 0xffff0000, v24
	v_lshlrev_b32_e32 v66, 16, v25
	v_and_b32_e32 v67, 0xffff0000, v25
	v_lshlrev_b32_e32 v68, 16, v26
	v_and_b32_e32 v69, 0xffff0000, v26
	v_lshlrev_b32_e32 v70, 16, v27
	v_and_b32_e32 v71, 0xffff0000, v27
	v_lshlrev_b32_e32 v72, 16, v28
	v_and_b32_e32 v73, 0xffff0000, v28
	v_lshlrev_b32_e32 v74, 16, v29
	v_and_b32_e32 v75, 0xffff0000, v29
	v_lshlrev_b32_e32 v76, 16, v30
	v_and_b32_e32 v77, 0xffff0000, v30
	v_lshlrev_b32_e32 v78, 16, v31
	v_and_b32_e32 v79, 0xffff0000, v31
	s_lshl_b32 s1, s0, 11
	v_add_u32_e32 v90, s1, v93
	s_add_u32 s1, s0, s98
	s_add_u32 s1, s1, s98
	s_min_u32 s1, s1, 0xffff
	s_lshl_b32 s1, s1, 11
	v_add_u32_e32 v91, s1, v93
	global_load_dwordx4 v[16:19], v91, s[4:5]
	global_load_dwordx4 v[20:23], v91, s[4:5] offset:1024
	global_load_dwordx4 v[24:27], v91, s[6:7]
	global_load_dwordx4 v[28:31], v91, s[6:7] offset:1024
	v_mul_f32_e32 v80, v48, v48
	v_mul_f32_e32 v81, v49, v49
	v_fmac_f32_e32 v80, v50, v50
	v_fmac_f32_e32 v81, v51, v51
	v_fmac_f32_e32 v80, v52, v52
	v_fmac_f32_e32 v81, v53, v53
	v_fmac_f32_e32 v80, v54, v54
	v_fmac_f32_e32 v81, v55, v55
	v_fmac_f32_e32 v80, v56, v56
	v_fmac_f32_e32 v81, v57, v57
	v_fmac_f32_e32 v80, v58, v58
	v_fmac_f32_e32 v81, v59, v59
	v_fmac_f32_e32 v80, v60, v60
	v_fmac_f32_e32 v81, v61, v61
	v_fmac_f32_e32 v80, v62, v62
	v_fmac_f32_e32 v81, v63, v63
	v_add_f32_e32 v80, v80, v81
	s_nop 1
	v_add_f32_dpp v80, v80, v80 quad_perm:[1,0,3,2] row_mask:0xf bank_mask:0xf
	s_nop 1
	v_add_f32_dpp v80, v80, v80 quad_perm:[2,3,0,1] row_mask:0xf bank_mask:0xf
	s_nop 1
	v_add_f32_dpp v80, v80, v80 row_half_mirror row_mask:0xf bank_mask:0xf
	s_nop 1
	v_add_f32_dpp v80, v80, v80 row_mirror row_mask:0xf bank_mask:0xf
	s_nop 1
	v_add_f32_dpp v80, v80, v80 row_bcast:15 row_mask:0xa bank_mask:0xf
	s_nop 1
	v_add_f32_dpp v80, v80, v80 row_bcast:31 row_mask:0xc bank_mask:0xf
	s_nop 1
	v_readlane_b32 s1, v80, 63
	s_nop 1
	v_mov_b32_e32 v80, s1
	v_fmamk_f32 v80, v80, 0x3a800000, v229
	v_rsq_f32_e32 v80, v80
	s_nop 0
	v_mul_f32_e32 v48, v80, v48
	v_mul_f32_e32 v49, v80, v49
	v_mul_f32_e32 v50, v80, v50
	v_mul_f32_e32 v51, v80, v51
	v_mul_f32_e32 v52, v80, v52
	v_mul_f32_e32 v53, v80, v53
	v_mul_f32_e32 v54, v80, v54
	v_mul_f32_e32 v55, v80, v55
	v_mul_f32_e32 v56, v80, v56
	v_mul_f32_e32 v57, v80, v57
	v_mul_f32_e32 v58, v80, v58
	v_mul_f32_e32 v59, v80, v59
	v_mul_f32_e32 v60, v80, v60
	v_mul_f32_e32 v61, v80, v61
	v_mul_f32_e32 v62, v80, v62
	v_mul_f32_e32 v63, v80, v63
	v_fmac_f32_e32 v64, v100, v48
	v_fmac_f32_e32 v65, v101, v49
	v_fmac_f32_e32 v66, v102, v50
	v_fmac_f32_e32 v67, v103, v51
	v_fmac_f32_e32 v68, v104, v52
	v_fmac_f32_e32 v69, v105, v53
	v_fmac_f32_e32 v70, v106, v54
	v_fmac_f32_e32 v71, v107, v55
	v_fmac_f32_e32 v72, v108, v56
	v_fmac_f32_e32 v73, v109, v57
	v_fmac_f32_e32 v74, v110, v58
	v_fmac_f32_e32 v75, v111, v59
	v_fmac_f32_e32 v76, v112, v60
	v_fmac_f32_e32 v77, v113, v61
	v_fmac_f32_e32 v78, v114, v62
	v_fmac_f32_e32 v79, v115, v63
	v_cvt_pk_bf16_f32 v82, v64, v65
	v_cvt_pk_bf16_f32 v83, v66, v67
	v_cvt_pk_bf16_f32 v84, v68, v69
	v_cvt_pk_bf16_f32 v85, v70, v71
	v_cvt_pk_bf16_f32 v86, v72, v73
	v_cvt_pk_bf16_f32 v87, v74, v75
	v_cvt_pk_bf16_f32 v88, v76, v77
	v_cvt_pk_bf16_f32 v89, v78, v79
	global_store_dwordx4 v90, v[82:85], s[6:7]
	global_store_dwordx4 v90, v[86:89], s[6:7] offset:1024
	v_mul_f32_e32 v80, v64, v64
	v_mul_f32_e32 v81, v65, v65
	v_fmac_f32_e32 v80, v66, v66
	v_fmac_f32_e32 v81, v67, v67
	v_fmac_f32_e32 v80, v68, v68
	v_fmac_f32_e32 v81, v69, v69
	v_fmac_f32_e32 v80, v70, v70
	v_fmac_f32_e32 v81, v71, v71
	v_fmac_f32_e32 v80, v72, v72
	v_fmac_f32_e32 v81, v73, v73
	v_fmac_f32_e32 v80, v74, v74
	v_fmac_f32_e32 v81, v75, v75
	v_fmac_f32_e32 v80, v76, v76
	v_fmac_f32_e32 v81, v77, v77
	v_fmac_f32_e32 v80, v78, v78
	v_fmac_f32_e32 v81, v79, v79
	v_add_f32_e32 v80, v80, v81
	s_nop 1
	v_add_f32_dpp v80, v80, v80 quad_perm:[1,0,3,2] row_mask:0xf bank_mask:0xf
	s_nop 1
	v_add_f32_dpp v80, v80, v80 quad_perm:[2,3,0,1] row_mask:0xf bank_mask:0xf
	s_nop 1
	v_add_f32_dpp v80, v80, v80 row_half_mirror row_mask:0xf bank_mask:0xf
	s_nop 1
	v_add_f32_dpp v80, v80, v80 row_mirror row_mask:0xf bank_mask:0xf
	s_nop 1
	v_add_f32_dpp v80, v80, v80 row_bcast:15 row_mask:0xa bank_mask:0xf
	s_nop 1
	v_add_f32_dpp v80, v80, v80 row_bcast:31 row_mask:0xc bank_mask:0xf
	s_nop 1
	v_readlane_b32 s1, v80, 63
	s_nop 1
	v_mov_b32_e32 v80, s1
	v_fmamk_f32 v80, v80, 0x3a800000, v229
	v_rsq_f32_e32 v80, v80
	s_lshl_b32 s1, s0, 2
	s_add_u32 s1, s1, 0x1b10e000
	v_mov_b32_e32 v92, s1
	s_mov_b64 exec, 1
	global_store_dword v92, v80, s[86:87]
	s_mov_b64 exec, -1
	s_add_u32 s0, s0, s98
	s_cmp_gt_u32 s0, 0xffff
	s_cbranch_scc1 .Lresid_a_done
	s_cmp_eq_u32 s99, 1
	s_cbranch_scc1 .Lresid_a_1_wfirst
	s_waitcnt vmcnt(10)
	s_branch .Lresid_a_1_wdone

; DI void phase_resid(const float* x_f32, bf16_t* xb, const bf16_t* y, const float* g_post, float* out_f32, float* rstd_out, bool write_xb) {
;     ...
;   for (int row = gw; row < T_TOK; row += nw) {
;     float xv[2][8];
; #pragma unroll
;     for (int j = 0; j < 2; ++j) {
;       const size_t off = (size_t)row * 1024 + j * 512 + lane * 8;
;       if (x_f32) {
;         const float4 a = *(const float4*)(x_f32 + off), c = *(const float4*)(x_f32 + off + 4);
;         xv[j][0] = a.x; xv[j][1] = a.y; xv[j][2] = a.z; xv[j][3] = a.w; xv[j][4] = c.x; xv[j][5] = c.y; xv[j][6] = c.z; xv[j][7] = c.w;
;       } else {
;         const uint4 u = *(const uint4*)(xb + off);
;         xv[j][0] = bf_lo(u.x); xv[j][1] = bf_hi(u.x); xv[j][2] = bf_lo(u.y); xv[j][3] = bf_hi(u.y);
;         xv[j][4] = bf_lo(u.z); xv[j][5] = bf_hi(u.z); xv[j][6] = bf_lo(u.w); xv[j][7] = bf_hi(u.w);
;       }
;     }
;     if (y) {
;       float yv[2][8];
;       float ss = 0.f;
; #pragma unroll
;       for (int j = 0; j < 2; ++j) {
;         const uint4 u = *(const uint4*)(y + (size_t)row * 1024 + j * 512 + lane * 8);
;         yv[j][0] = bf_lo(u.x); yv[j][1] = bf_hi(u.x); yv[j][2] = bf_lo(u.y); yv[j][3] = bf_hi(u.y);
;         yv[j][4] = bf_lo(u.z); yv[j][5] = bf_hi(u.z); yv[j][6] = bf_lo(u.w); yv[j][7] = bf_hi(u.w);
; #pragma unroll
;         for (int e = 0; e < 8; ++e) ss += yv[j][e] * yv[j][e];
;       }
;       ss = wave_sum(ss);
;       const float rs = frsq(ss * (1.f / 1024.f) + EPS);
; #pragma unroll
;       for (int j = 0; j < 2; ++j) {
;         const float4 g0 = *(const float4*)(g_post + j * 512 + lane * 8), g1 = *(const float4*)(g_post + j * 512 + lane * 8 + 4);
;         xv[j][0] += yv[j][0] * rs * g0.x; xv[j][1] += yv[j][1] * rs * g0.y; xv[j][2] += yv[j][2] * rs * g0.z; xv[j][3] += yv[j][3] * rs * g0.w;
;         xv[j][4] += yv[j][4] * rs * g1.x; xv[j][5] += yv[j][5] * rs * g1.y; xv[j][6] += yv[j][6] * rs * g1.z; xv[j][7] += yv[j][7] * rs * g1.w;
;       }
;     }
;     if (out_f32) {
; #pragma unroll
;       for (int j = 0; j < 2; ++j) {
;         const size_t off = (size_t)row * 1024 + j * 512 + lane * 8;
;         *(float4*)(out_f32 + off) = make_float4(xv[j][0], xv[j][1], xv[j][2], xv[j][3]);
;         *(float4*)(out_f32 + off + 4) = make_float4(xv[j][4], xv[j][5], xv[j][6], xv[j][7]);
;       }
;     }
;     if (write_xb) {
; #pragma unroll
;       for (int j = 0; j < 2; ++j) {
.Lresid_a_1_wdone:
	v_lshlrev_b32_e32 v48, 16, v32
	v_and_b32_e32 v49, 0xffff0000, v32
	v_lshlrev_b32_e32 v50, 16, v33
	v_and_b32_e32 v51, 0xffff0000, v33
	v_lshlrev_b32_e32 v52, 16, v34
	v_and_b32_e32 v53, 0xffff0000, v34
	v_lshlrev_b32_e32 v54, 16, v35
	v_and_b32_e32 v55, 0xffff0000, v35
	v_lshlrev_b32_e32 v56, 16, v36
	v_and_b32_e32 v57, 0xffff0000, v36
	v_lshlrev_b32_e32 v58, 16, v37
	v_and_b32_e32 v59, 0xffff0000, v37
	v_lshlrev_b32_e32 v60, 16, v38
	v_and_b32_e32 v61, 0xffff0000, v38
	v_lshlrev_b32_e32 v62, 16, v39
	v_and_b32_e32 v63, 0xffff0000, v39
	v_lshlrev_b32_e32 v64, 16, v40
	v_and_b32_e32 v65, 0xffff0000, v40
	v_lshlrev_b32_e32 v66, 16, v41
	v_and_b32_e32 v67, 0xffff0000, v41
	v_lshlrev_b32_e32 v68, 16, v42
	v_and_b32_e32 v69, 0xffff0000, v42
	v_lshlrev_b32_e32 v70, 16, v43
	v_and_b32_e32 v71, 0xffff0000, v43
	v_lshlrev_b32_e32 v72, 16, v44
	v_and_b32_e32 v73, 0xffff0000, v44
	v_lshlrev_b32_e32 v74, 16, v45
	v_and_b32_e32 v75, 0xffff0000, v45
	v_lshlrev_b32_e32 v76, 16, v46
	v_and_b32_e32 v77, 0xffff0000, v46
	v_lshlrev_b32_e32 v78, 16, v47
	v_and_b32_e32 v79, 0xffff0000, v47
	s_lshl_b32 s1, s0, 11
	v_add_u32_e32 v90, s1, v93
	s_add_u32 s1, s0, s98
	s_add_u32 s1, s1, s98
	s_min_u32 s1, s1, 0xffff
	s_lshl_b32 s1, s1, 11
	v_add_u32_e32 v91, s1, v93
	global_load_dwordx4 v[32:35], v91, s[4:5]
	global_load_dwordx4 v[36:39], v91, s[4:5] offset:1024
	global_load_dwordx4 v[40:43], v91, s[6:7]
	global_load_dwordx4 v[44:47], v91, s[6:7] offset:1024
	v_mul_f32_e32 v80, v48, v48
	v_mul_f32_e32 v81, v49, v49
	v_fmac_f32_e32 v80, v50, v50
	v_fmac_f32_e32 v81, v51, v51
	v_fmac_f32_e32 v80, v52, v52
	v_fmac_f32_e32 v81, v53, v53
	v_fmac_f32_e32 v80, v54, v54
	v_fmac_f32_e32 v81, v55, v55
	v_fmac_f32_e32 v80, v56, v56
	v_fmac_f32_e32 v81, v57, v57
	v_fmac_f32_e32 v80, v58, v58
	v_fmac_f32_e32 v81, v59, v59
	v_fmac_f32_e32 v80, v60, v60
	v_fmac_f32_e32 v81, v61, v61
	v_fmac_f32_e32 v80, v62, v62
	v_fmac_f32_e32 v81, v63, v63
	v_add_f32_e32 v80, v80, v81
	s_nop 1
	v_add_f32_dpp v80, v80, v80 quad_perm:[1,0,3,2] row_mask:0xf bank_mask:0xf
	s_nop 1
	v_add_f32_dpp v80, v80, v80 quad_perm:[2,3,0,1] row_mask:0xf bank_mask:0xf
	s_nop 1
	v_add_f32_dpp v80, v80, v80 row_half_mirror row_mask:0xf bank_mask:0xf
	s_nop 1
	v_add_f32_dpp v80, v80, v80 row_mirror row_mask:0xf bank_mask:0xf
	s_nop 1
	v_add_f32_dpp v80, v80, v80 row_bcast:15 row_mask:0xa bank_mask:0xf
	s_nop 1
	v_add_f32_dpp v80, v80, v80 row_bcast:31 row_mask:0xc bank_mask:0xf
	s_nop 1
	v_readlane_b32 s1, v80, 63
	s_nop 1
	v_mov_b32_e32 v80, s1
	v_fmamk_f32 v80, v80, 0x3a800000, v229
	v_rsq_f32_e32 v80, v80
	s_nop 0
	v_mul_f32_e32 v48, v80, v48
	v_mul_f32_e32 v49, v80, v49
	v_mul_f32_e32 v50, v80, v50
	v_mul_f32_e32 v51, v80, v51
	v_mul_f32_e32 v52, v80, v52
	v_mul_f32_e32 v53, v80, v53
	v_mul_f32_e32 v54, v80, v54
	v_mul_f32_e32 v55, v80, v55
	v_mul_f32_e32 v56, v80, v56
	v_mul_f32_e32 v57, v80, v57
	v_mul_f32_e32 v58, v80, v58
	v_mul_f32_e32 v59, v80, v59
	v_mul_f32_e32 v60, v80, v60
	v_mul_f32_e32 v61, v80, v61
	v_mul_f32_e32 v62, v80, v62
	v_mul_f32_e32 v63, v80, v63
	v_fmac_f32_e32 v64, v100, v48
	v_fmac_f32_e32 v65, v101, v49
	v_fmac_f32_e32 v66, v102, v50
	v_fmac_f32_e32 v67, v103, v51
	v_fmac_f32_e32 v68, v104, v52
	v_fmac_f32_e32 v69, v105, v53
	v_fmac_f32_e32 v70, v106, v54
	v_fmac_f32_e32 v71, v107, v55
	v_fmac_f32_e32 v72, v108, v56
	v_fmac_f32_e32 v73, v109, v57
	v_fmac_f32_e32 v74, v110, v58
	v_fmac_f32_e32 v75, v111, v59
	v_fmac_f32_e32 v76, v112, v60
	v_fmac_f32_e32 v77, v113, v61
	v_fmac_f32_e32 v78, v114, v62
	v_fmac_f32_e32 v79, v115, v63
	v_cvt_pk_bf16_f32 v82, v64, v65
	v_cvt_pk_bf16_f32 v83, v66, v67
	v_cvt_pk_bf16_f32 v84, v68, v69
	v_cvt_pk_bf16_f32 v85, v70, v71
	v_cvt_pk_bf16_f32 v86, v72, v73
	v_cvt_pk_bf16_f32 v87, v74, v75
	v_cvt_pk_bf16_f32 v88, v76, v77
	v_cvt_pk_bf16_f32 v89, v78, v79
	global_store_dwordx4 v90, v[82:85], s[6:7]
	global_store_dwordx4 v90, v[86:89], s[6:7] offset:1024
	v_mul_f32_e32 v80, v64, v64
	v_mul_f32_e32 v81, v65, v65
	v_fmac_f32_e32 v80, v66, v66
	v_fmac_f32_e32 v81, v67, v67
	v_fmac_f32_e32 v80, v68, v68
	v_fmac_f32_e32 v81, v69, v69
	v_fmac_f32_e32 v80, v70, v70
	v_fmac_f32_e32 v81, v71, v71
	v_fmac_f32_e32 v80, v72, v72
	v_fmac_f32_e32 v81, v73, v73
	v_fmac_f32_e32 v80, v74, v74
	v_fmac_f32_e32 v81, v75, v75
	v_fmac_f32_e32 v80, v76, v76
	v_fmac_f32_e32 v81, v77, v77
	v_fmac_f32_e32 v80, v78, v78
	v_fmac_f32_e32 v81, v79, v79
	v_add_f32_e32 v80, v80, v81
	s_nop 1
	v_add_f32_dpp v80, v80, v80 quad_perm:[1,0,3,2] row_mask:0xf bank_mask:0xf
	s_nop 1
	v_add_f32_dpp v80, v80, v80 quad_perm:[2,3,0,1] row_mask:0xf bank_mask:0xf
	s_nop 1
	v_add_f32_dpp v80, v80, v80 row_half_mirror row_mask:0xf bank_mask:0xf
	s_nop 1
	v_add_f32_dpp v80, v80, v80 row_mirror row_mask:0xf bank_mask:0xf
	s_nop 1
	v_add_f32_dpp v80, v80, v80 row_bcast:15 row_mask:0xa bank_mask:0xf
	s_nop 1
	v_add_f32_dpp v80, v80, v80 row_bcast:31 row_mask:0xc bank_mask:0xf
	s_nop 1
	v_readlane_b32 s1, v80, 63
	s_nop 1
	v_mov_b32_e32 v80, s1
	v_fmamk_f32 v80, v80, 0x3a800000, v229
	v_rsq_f32_e32 v80, v80
	s_lshl_b32 s1, s0, 2
	s_add_u32 s1, s1, 0x1b10e000
	v_mov_b32_e32 v92, s1
	s_mov_b64 exec, 1
	global_store_dword v92, v80, s[86:87]
	s_mov_b64 exec, -1
	s_add_u32 s0, s0, s98
	s_cmp_gt_u32 s0, 0xffff
	s_cbranch_scc1 .Lresid_a_done
	s_mov_b32 s99, 0
	s_branch .Lresid_a_loop
.Lresid_a_done:
	s_waitcnt vmcnt(0)
.LBB0_27:
	s_or_b64 exec, exec, s[2:3]

; #define PG8_STAGE(bufoff, gbase, voff) do { _Pragma("unroll") for (int _i = 0; _i < 2; ++_i) \
;     __builtin_amdgcn_global_load_lds((const unsigned*)((const char*)(gbase) + (voff)[_i]), (PG8_LAS unsigned*)(lds + (bufoff) + ldsw + _i * 8192), 16, 0, 0); } while (0)
; #define PG8_LDA(dst, b, h) do { _Pragma("unroll") for (int m = 0; m < 4; ++m) _Pragma("unroll") for (int k = 0; k < 2; ++k) dst[m][k] = *(const PG8_LAS bf16x8*)(lds + PG8_SA(b, h) + aoff + m * 2048 + k * 1024); } while (0)
; #define PG8_LDB(dst, b, h) do { _Pragma("unroll") for (int n = 0; n < 2; ++n) _Pragma("unroll") for (int k = 0; k < 2; ++k) dst[n][k] = *(const PG8_LAS bf16x8*)(lds + PG8_SB(b, h) + boff + n * 2048 + k * 1024); } while (0)
; #define PG8_WAIT_V(n) asm volatile("s_waitcnt vmcnt(" #n ")" ::: "memory")
; template <class Epi>
; DI void gemm_phase(PG8_LAS unsigned char* lds, const Gemm g, const StaticOrder& S, const Epi& E) {
;     ...
;     for (int t = 0; t < nt; t += 2) {
;       const bool last = (t == nt - 2);
;       const char* a1 = cA + (size_t)(t + 1) * kstepA;
;       const char* a2 = last ? nA : cA + (size_t)(t + 2) * kstepA; const char* b2 = last ? nB : cB + (size_t)(t + 2) * kstep;
;       const char* a3 = a2 + kstepA; const char* b3 = b2 + kstep;
;       PG8_LDB(B0, 0, 0); PG8_SCHED; PG8_LDA(At, 0, 0); PG8_STAGE(PG8_SA(1, 1), a1 + hstepA, voffA);
;       PG8_WAIT_L(8); PG8_BAR; PG8_WAIT_L(0); PG8_MMA(0, 0, At, B0); PG8_BAR; PG8_SCHED;
;       PG8_LDB(B1, 0, 1); PG8_STAGE(PG8_SB(0, 0), b2, voffB);
;       PG8_BAR; PG8_WAIT_L(0); PG8_MMA(0, 1, At, B1); PG8_BAR;
;       PG8_LDA(At, 0, 1); PG8_STAGE(PG8_SA(0, 0), a2, voffA);
;       PG8_BAR; PG8_WAIT_L(0); PG8_MMA(1, 0, At, B0); PG8_BAR; PG8_SCHED;
;       PG8_STAGE(PG8_SB(0, 1), b2 + hstepB, voffB);
;       PG8_WAIT_V(6); PG8_BAR; PG8_MMA(1, 1, At, B1); PG8_BAR;
;       PG8_LDB(B0, 1, 0); PG8_SCHED; PG8_LDA(At, 1, 0); PG8_STAGE(PG8_SA(0, 1), a2 + hstepA, voffA);
;       PG8_WAIT_L(8); PG8_BAR; PG8_WAIT_L(0); PG8_MMA(0, 0, At, B0); PG8_BAR; PG8_SCHED;
;       PG8_LDB(B1, 1, 1); PG8_STAGE(PG8_SB(1, 0), b3, voffB);
;       PG8_BAR; PG8_WAIT_L(0); PG8_MMA(0, 1, At, B1); PG8_BAR;
;       PG8_LDA(At, 1, 1); PG8_STAGE(PG8_SA(1, 0), a3, voffA);
;       PG8_BAR; PG8_WAIT_L(0); PG8_MMA(1, 0, At, B0); PG8_BAR; PG8_SCHED;
;       PG8_STAGE(PG8_SB(1, 1), b3 + hstepB, voffB);
;       PG8_WAIT_V(6); PG8_BAR; PG8_MMA(1, 1, At, B1); PG8_BAR;
.LBB0_69:
	s_add_u32 s10, s8, 0xfffc0080
	s_addc_u32 s11, s9, -1
	s_add_i32 s55, 0, 0x10000
	v_add_u32_e32 v0, s55, v147
	ds_read_b128 v[150:153], v0
	ds_read_b128 v[154:157], v0 offset:1024
	ds_read_b128 v[158:161], v0 offset:2048
	ds_read_b128 v[162:165], v0 offset:3072
	s_cmp_eq_u32 s54, 12
	s_cselect_b32 s29, s3, s11
	s_cselect_b32 s28, s50, s10
	s_cselect_b32 s11, s1, s53
	s_cselect_b32 s10, s51, s52
	v_lshl_add_u64 v[144:145], s[8:9], 0, v[138:139]
	s_add_i32 m0, s38, 0xc000
	ds_read_b128 v[168:171], v148
	ds_read_b128 v[172:175], v148 offset:1024
	ds_read_b128 v[176:179], v148 offset:2048
	ds_read_b128 v[180:183], v148 offset:3072
	ds_read_b128 v[184:187], v148 offset:4096
	ds_read_b128 v[188:191], v148 offset:5120
	ds_read_b128 v[192:195], v148 offset:6144
	ds_read_b128 v[196:199], v148 offset:7168
	global_load_lds_dwordx4 v[144:145], off
	v_lshl_add_u64 v[144:145], s[8:9], 0, v[140:141]
	s_add_i32 m0, s38, 0xe000
	s_nop 0
	global_load_lds_dwordx4 v[144:145], off
	s_waitcnt lgkmcnt(8)
	s_barrier
	s_waitcnt lgkmcnt(0)
	s_setprio 1
	s_waitcnt lgkmcnt(0)
	v_mfma_f32_16x16x32_bf16 v[126:129], v[150:153], v[168:171], v[126:129]
	v_mfma_f32_16x16x32_bf16 v[122:125], v[158:161], v[168:171], v[122:125]
	v_mfma_f32_16x16x32_bf16 v[110:113], v[150:153], v[176:179], v[110:113]
	v_mfma_f32_16x16x32_bf16 v[106:109], v[158:161], v[176:179], v[106:109]
	v_mfma_f32_16x16x32_bf16 v[94:97], v[150:153], v[184:187], v[94:97]
	v_mfma_f32_16x16x32_bf16 v[90:93], v[158:161], v[184:187], v[90:93]
	v_mfma_f32_16x16x32_bf16 v[78:81], v[150:153], v[192:195], v[78:81]
	v_mfma_f32_16x16x32_bf16 v[74:77], v[158:161], v[192:195], v[74:77]
	v_mfma_f32_16x16x32_bf16 v[126:129], v[154:157], v[172:175], v[126:129]
	v_mfma_f32_16x16x32_bf16 v[122:125], v[162:165], v[172:175], v[122:125]
	v_mfma_f32_16x16x32_bf16 v[110:113], v[154:157], v[180:183], v[110:113]
	v_mfma_f32_16x16x32_bf16 v[106:109], v[162:165], v[180:183], v[106:109]
	v_mfma_f32_16x16x32_bf16 v[94:97], v[154:157], v[188:191], v[94:97]
	v_mfma_f32_16x16x32_bf16 v[90:93], v[162:165], v[188:191], v[90:93]
	v_mfma_f32_16x16x32_bf16 v[78:81], v[154:157], v[196:199], v[78:81]
	v_mfma_f32_16x16x32_bf16 v[74:77], v[162:165], v[196:199], v[74:77]
	s_setprio 0
	s_barrier
	s_add_i32 s58, 0, 0x14000
	s_add_i32 s55, s55, s36
	v_add_u32_e32 v0, s58, v147
	v_lshl_add_u64 v[144:145], s[10:11], 0, v[132:133]
	s_mov_b32 m0, s55
	ds_read_b128 v[200:203], v0
	ds_read_b128 v[204:207], v0 offset:1024
	ds_read_b128 v[208:211], v0 offset:2048
	ds_read_b128 v[212:215], v0 offset:3072
	global_load_lds_dwordx4 v[144:145], off
	v_lshl_add_u64 v[166:167], s[10:11], 0, v[136:137]
	s_add_i32 m0, s55, 0x2000
	s_nop 0
	global_load_lds_dwordx4 v[166:167], off
	s_barrier
	s_waitcnt lgkmcnt(0)
	s_setprio 1
	s_waitcnt lgkmcnt(0)
	v_mfma_f32_16x16x32_bf16 v[118:121], v[200:203], v[168:171], v[118:121]
	v_mfma_f32_16x16x32_bf16 v[114:117], v[208:211], v[168:171], v[114:117]
	v_mfma_f32_16x16x32_bf16 v[102:105], v[200:203], v[176:179], v[102:105]
	v_mfma_f32_16x16x32_bf16 v[98:101], v[208:211], v[176:179], v[98:101]
	v_mfma_f32_16x16x32_bf16 v[86:89], v[200:203], v[184:187], v[86:89]
	v_mfma_f32_16x16x32_bf16 v[82:85], v[208:211], v[184:187], v[82:85]
	v_mfma_f32_16x16x32_bf16 v[70:73], v[200:203], v[192:195], v[70:73]
	v_mfma_f32_16x16x32_bf16 v[66:69], v[208:211], v[192:195], v[66:69]
	v_mfma_f32_16x16x32_bf16 v[118:121], v[204:207], v[172:175], v[118:121]
	v_mfma_f32_16x16x32_bf16 v[114:117], v[212:215], v[172:175], v[114:117]
	v_mfma_f32_16x16x32_bf16 v[102:105], v[204:207], v[180:183], v[102:105]
	v_mfma_f32_16x16x32_bf16 v[98:101], v[212:215], v[180:183], v[98:101]
	v_mfma_f32_16x16x32_bf16 v[86:89], v[204:207], v[188:191], v[86:89]
	v_mfma_f32_16x16x32_bf16 v[82:85], v[212:215], v[188:191], v[82:85]
	v_mfma_f32_16x16x32_bf16 v[70:73], v[204:207], v[196:199], v[70:73]
	v_mfma_f32_16x16x32_bf16 v[66:69], v[212:215], v[196:199], v[66:69]
	s_setprio 0
	s_mov_b32 m0, s38
	v_lshl_add_u64 v[216:217], s[28:29], 0, v[130:131]
	s_barrier
	ds_read_b128 v[168:171], v148 offset:16384
	ds_read_b128 v[172:175], v148 offset:17408
	ds_read_b128 v[176:179], v148 offset:18432
	ds_read_b128 v[180:183], v148 offset:19456
	ds_read_b128 v[184:187], v148 offset:20480
	ds_read_b128 v[188:191], v148 offset:21504
	ds_read_b128 v[192:195], v148 offset:22528
	ds_read_b128 v[196:199], v148 offset:23552
	global_load_lds_dwordx4 v[216:217], off
	v_lshl_add_u64 v[218:219], s[28:29], 0, v[134:135]
	s_mov_b32 m0, s39
	s_nop 0
	global_load_lds_dwordx4 v[218:219], off
	s_barrier
	s_waitcnt lgkmcnt(0)
	s_setprio 1
	s_waitcnt lgkmcnt(0)
	v_mfma_f32_16x16x32_bf16 v[62:65], v[150:153], v[168:171], v[62:65]
	v_mfma_f32_16x16x32_bf16 v[58:61], v[158:161], v[168:171], v[58:61]
	v_mfma_f32_16x16x32_bf16 v[46:49], v[150:153], v[176:179], v[46:49]
	v_mfma_f32_16x16x32_bf16 v[42:45], v[158:161], v[176:179], v[42:45]
	v_mfma_f32_16x16x32_bf16 v[30:33], v[150:153], v[184:187], v[30:33]
	v_mfma_f32_16x16x32_bf16 v[26:29], v[158:161], v[184:187], v[26:29]
	v_mfma_f32_16x16x32_bf16 v[14:17], v[150:153], v[192:195], v[14:17]
	v_mfma_f32_16x16x32_bf16 v[10:13], v[158:161], v[192:195], v[10:13]
	v_mfma_f32_16x16x32_bf16 v[62:65], v[154:157], v[172:175], v[62:65]
	v_mfma_f32_16x16x32_bf16 v[58:61], v[162:165], v[172:175], v[58:61]
	v_mfma_f32_16x16x32_bf16 v[46:49], v[154:157], v[180:183], v[46:49]
	v_mfma_f32_16x16x32_bf16 v[42:45], v[162:165], v[180:183], v[42:45]
	v_mfma_f32_16x16x32_bf16 v[30:33], v[154:157], v[188:191], v[30:33]
	v_mfma_f32_16x16x32_bf16 v[26:29], v[162:165], v[188:191], v[26:29]
	v_mfma_f32_16x16x32_bf16 v[14:17], v[154:157], v[196:199], v[14:17]
	v_mfma_f32_16x16x32_bf16 v[10:13], v[162:165], v[196:199], v[10:13]
	s_setprio 0
	s_barrier
; #define PG8_STAGE(bufoff, gbase, voff) do { _Pragma("unroll") for (int _i = 0; _i < 2; ++_i) \
;     __builtin_amdgcn_global_load_lds((const unsigned*)((const char*)(gbase) + (voff)[_i]), (PG8_LAS unsigned*)(lds + (bufoff) + ldsw + _i * 8192), 16, 0, 0); } while (0)
; #define PG8_LDA(dst, b, h) do { _Pragma("unroll") for (int m = 0; m < 4; ++m) _Pragma("unroll") for (int k = 0; k < 2; ++k) dst[m][k] = *(const PG8_LAS bf16x8*)(lds + PG8_SA(b, h) + aoff + m * 2048 + k * 1024); } while (0)
; #define PG8_LDB(dst, b, h) do { _Pragma("unroll") for (int n = 0; n < 2; ++n) _Pragma("unroll") for (int k = 0; k < 2; ++k) dst[n][k] = *(const PG8_LAS bf16x8*)(lds + PG8_SB(b, h) + boff + n * 2048 + k * 1024); } while (0)
; #define PG8_WAIT_V(n) asm volatile("s_waitcnt vmcnt(" #n ")" ::: "memory")
; template <class Epi>
; DI void gemm_phase(PG8_LAS unsigned char* lds, const Gemm g, const StaticOrder& S, const Epi& E) {
;     ...
;     for (int t = 0; t < nt; t += 2) {
;       const bool last = (t == nt - 2);
;       const char* a1 = cA + (size_t)(t + 1) * kstepA;
;       const char* a2 = last ? nA : cA + (size_t)(t + 2) * kstepA; const char* b2 = last ? nB : cB + (size_t)(t + 2) * kstep;
;       const char* a3 = a2 + kstepA; const char* b3 = b2 + kstep;
;       PG8_LDB(B0, 0, 0); PG8_SCHED; PG8_LDA(At, 0, 0); PG8_STAGE(PG8_SA(1, 1), a1 + hstepA, voffA);
;       PG8_WAIT_L(8); PG8_BAR; PG8_WAIT_L(0); PG8_MMA(0, 0, At, B0); PG8_BAR; PG8_SCHED;
;       PG8_LDB(B1, 0, 1); PG8_STAGE(PG8_SB(0, 0), b2, voffB);
;       PG8_BAR; PG8_WAIT_L(0); PG8_MMA(0, 1, At, B1); PG8_BAR;
;       PG8_LDA(At, 0, 1); PG8_STAGE(PG8_SA(0, 0), a2, voffA);
;       PG8_BAR; PG8_WAIT_L(0); PG8_MMA(1, 0, At, B0); PG8_BAR; PG8_SCHED;
;       PG8_STAGE(PG8_SB(0, 1), b2 + hstepB, voffB);
;       PG8_WAIT_V(6); PG8_BAR; PG8_MMA(1, 1, At, B1); PG8_BAR;
;       PG8_LDB(B0, 1, 0); PG8_SCHED; PG8_LDA(At, 1, 0); PG8_STAGE(PG8_SA(0, 1), a2 + hstepA, voffA);
;       PG8_WAIT_L(8); PG8_BAR; PG8_WAIT_L(0); PG8_MMA(0, 0, At, B0); PG8_BAR; PG8_SCHED;
;       PG8_LDB(B1, 1, 1); PG8_STAGE(PG8_SB(1, 0), b3, voffB);
;       PG8_BAR; PG8_WAIT_L(0); PG8_MMA(0, 1, At, B1); PG8_BAR;
;       PG8_LDA(At, 1, 1); PG8_STAGE(PG8_SA(1, 0), a3, voffA);
;       PG8_BAR; PG8_WAIT_L(0); PG8_MMA(1, 0, At, B0); PG8_BAR; PG8_SCHED;
;       PG8_STAGE(PG8_SB(1, 1), b3 + hstepB, voffB);
;       PG8_WAIT_V(6); PG8_BAR; PG8_MMA(1, 1, At, B1); PG8_BAR;
	s_add_u32 s56, s10, 0x10000
	s_addc_u32 s57, s11, 0
	s_add_i32 s55, s58, s36
	v_lshl_add_u64 v[150:151], s[56:57], 0, v[132:133]
	s_mov_b32 m0, s55
	s_nop 0
	global_load_lds_dwordx4 v[150:151], off
	v_lshl_add_u64 v[150:151], s[56:57], 0, v[136:137]
	s_add_i32 m0, s55, 0x2000
	s_nop 0
	global_load_lds_dwordx4 v[150:151], off
	s_waitcnt vmcnt(6)
	s_barrier
	s_setprio 1
	v_mfma_f32_16x16x32_bf16 v[54:57], v[200:203], v[168:171], v[54:57]
	v_mfma_f32_16x16x32_bf16 v[50:53], v[208:211], v[168:171], v[50:53]
	v_mfma_f32_16x16x32_bf16 v[38:41], v[200:203], v[176:179], v[38:41]
	v_mfma_f32_16x16x32_bf16 v[34:37], v[208:211], v[176:179], v[34:37]
	v_mfma_f32_16x16x32_bf16 v[22:25], v[200:203], v[184:187], v[22:25]
	v_mfma_f32_16x16x32_bf16 v[18:21], v[208:211], v[184:187], v[18:21]
	v_mfma_f32_16x16x32_bf16 v[6:9], v[200:203], v[192:195], v[6:9]
	v_mfma_f32_16x16x32_bf16 v[2:5], v[208:211], v[192:195], v[2:5]
	v_mfma_f32_16x16x32_bf16 v[54:57], v[204:207], v[172:175], v[54:57]
	v_mfma_f32_16x16x32_bf16 v[50:53], v[212:215], v[172:175], v[50:53]
	v_mfma_f32_16x16x32_bf16 v[38:41], v[204:207], v[180:183], v[38:41]
	v_mfma_f32_16x16x32_bf16 v[34:37], v[212:215], v[180:183], v[34:37]
	v_mfma_f32_16x16x32_bf16 v[22:25], v[204:207], v[188:191], v[22:25]
	v_mfma_f32_16x16x32_bf16 v[18:21], v[212:215], v[188:191], v[18:21]
	v_mfma_f32_16x16x32_bf16 v[6:9], v[204:207], v[196:199], v[6:9]
	v_mfma_f32_16x16x32_bf16 v[2:5], v[212:215], v[196:199], v[2:5]
	s_setprio 0
	s_add_i32 s55, 0, 0x18000
	v_add_u32_e32 v0, s55, v147
	s_barrier
	ds_read_b128 v[150:153], v0
	ds_read_b128 v[154:157], v0 offset:1024
	ds_read_b128 v[158:161], v0 offset:2048
	ds_read_b128 v[162:165], v0 offset:3072
	s_add_u32 s28, s28, 0x40000
	s_addc_u32 s29, s29, 0
	s_mov_b32 m0, s40
	v_lshl_add_u64 v[200:201], s[28:29], 0, v[130:131]
	ds_read_b128 v[168:171], v148 offset:32768
	ds_read_b128 v[172:175], v148 offset:33792
	ds_read_b128 v[176:179], v148 offset:34816
	ds_read_b128 v[180:183], v148 offset:35840
	ds_read_b128 v[184:187], v148 offset:36864
	ds_read_b128 v[188:191], v148 offset:37888
	ds_read_b128 v[192:195], v148 offset:38912
	ds_read_b128 v[196:199], v148 offset:39936
	global_load_lds_dwordx4 v[200:201], off
	v_lshl_add_u64 v[200:201], s[28:29], 0, v[134:135]
	s_mov_b32 m0, s41
	s_nop 0
	global_load_lds_dwordx4 v[200:201], off
	s_waitcnt lgkmcnt(8)
	s_barrier
	s_waitcnt lgkmcnt(0)
	s_setprio 1
	s_waitcnt lgkmcnt(0)
	v_mfma_f32_16x16x32_bf16 v[126:129], v[150:153], v[168:171], v[126:129]
	v_mfma_f32_16x16x32_bf16 v[122:125], v[158:161], v[168:171], v[122:125]
	v_mfma_f32_16x16x32_bf16 v[110:113], v[150:153], v[176:179], v[110:113]
	v_mfma_f32_16x16x32_bf16 v[106:109], v[158:161], v[176:179], v[106:109]
	v_mfma_f32_16x16x32_bf16 v[94:97], v[150:153], v[184:187], v[94:97]
	v_mfma_f32_16x16x32_bf16 v[90:93], v[158:161], v[184:187], v[90:93]
	v_mfma_f32_16x16x32_bf16 v[78:81], v[150:153], v[192:195], v[78:81]
	v_mfma_f32_16x16x32_bf16 v[74:77], v[158:161], v[192:195], v[74:77]
	v_mfma_f32_16x16x32_bf16 v[126:129], v[154:157], v[172:175], v[126:129]
	v_mfma_f32_16x16x32_bf16 v[122:125], v[162:165], v[172:175], v[122:125]
	v_mfma_f32_16x16x32_bf16 v[110:113], v[154:157], v[180:183], v[110:113]
	v_mfma_f32_16x16x32_bf16 v[106:109], v[162:165], v[180:183], v[106:109]
	v_mfma_f32_16x16x32_bf16 v[94:97], v[154:157], v[188:191], v[94:97]
	v_mfma_f32_16x16x32_bf16 v[90:93], v[162:165], v[188:191], v[90:93]
	v_mfma_f32_16x16x32_bf16 v[78:81], v[154:157], v[196:199], v[78:81]
	v_mfma_f32_16x16x32_bf16 v[74:77], v[162:165], v[196:199], v[74:77]
	s_setprio 0
	s_barrier
	s_add_i32 s28, 0, 0x1c000
	s_add_i32 s29, s55, s36
	v_add_u32_e32 v0, s28, v147
	v_lshl_add_u64 v[144:145], v[144:145], 0, s[60:61]
	s_mov_b32 m0, s29
	ds_read_b128 v[200:203], v0
	ds_read_b128 v[204:207], v0 offset:1024
	ds_read_b128 v[208:211], v0 offset:2048
	ds_read_b128 v[212:215], v0 offset:3072
	global_load_lds_dwordx4 v[144:145], off
	v_lshl_add_u64 v[144:145], v[166:167], 0, s[60:61]
	s_add_i32 m0, s29, 0x2000
	s_nop 0
	global_load_lds_dwordx4 v[144:145], off
	s_barrier
	s_waitcnt lgkmcnt(0)
	s_setprio 1
	s_waitcnt lgkmcnt(0)
	v_mfma_f32_16x16x32_bf16 v[118:121], v[200:203], v[168:171], v[118:121]
	v_mfma_f32_16x16x32_bf16 v[114:117], v[208:211], v[168:171], v[114:117]
	v_mfma_f32_16x16x32_bf16 v[102:105], v[200:203], v[176:179], v[102:105]
	v_mfma_f32_16x16x32_bf16 v[98:101], v[208:211], v[176:179], v[98:101]
	v_mfma_f32_16x16x32_bf16 v[86:89], v[200:203], v[184:187], v[86:89]
	v_mfma_f32_16x16x32_bf16 v[82:85], v[208:211], v[184:187], v[82:85]
	v_mfma_f32_16x16x32_bf16 v[70:73], v[200:203], v[192:195], v[70:73]
	v_mfma_f32_16x16x32_bf16 v[66:69], v[208:211], v[192:195], v[66:69]
	v_mfma_f32_16x16x32_bf16 v[118:121], v[204:207], v[172:175], v[118:121]
	v_mfma_f32_16x16x32_bf16 v[114:117], v[212:215], v[172:175], v[114:117]
	v_mfma_f32_16x16x32_bf16 v[102:105], v[204:207], v[180:183], v[102:105]
	v_mfma_f32_16x16x32_bf16 v[98:101], v[212:215], v[180:183], v[98:101]
	v_mfma_f32_16x16x32_bf16 v[86:89], v[204:207], v[188:191], v[86:89]
	v_mfma_f32_16x16x32_bf16 v[82:85], v[212:215], v[188:191], v[82:85]
	v_mfma_f32_16x16x32_bf16 v[70:73], v[204:207], v[196:199], v[70:73]
	v_mfma_f32_16x16x32_bf16 v[66:69], v[212:215], v[196:199], v[66:69]
	s_setprio 0
	s_mov_b32 m0, s44
	v_lshl_add_u64 v[144:145], v[216:217], 0, s[60:61]
	s_barrier
	ds_read_b128 v[168:171], v148 offset:49152
	ds_read_b128 v[172:175], v148 offset:50176
	ds_read_b128 v[176:179], v148 offset:51200
	ds_read_b128 v[180:183], v148 offset:52224
	ds_read_b128 v[184:187], v148 offset:53248
	ds_read_b128 v[188:191], v148 offset:54272
	ds_read_b128 v[192:195], v148 offset:55296
	ds_read_b128 v[196:199], v148 offset:56320
	global_load_lds_dwordx4 v[144:145], off
	v_lshl_add_u64 v[144:145], v[218:219], 0, s[60:61]
	s_mov_b32 m0, s45
	s_nop 0
	global_load_lds_dwordx4 v[144:145], off
	s_barrier
; #define PG8_STAGE(bufoff, gbase, voff) do { _Pragma("unroll") for (int _i = 0; _i < 2; ++_i) \
;     __builtin_amdgcn_global_load_lds((const unsigned*)((const char*)(gbase) + (voff)[_i]), (PG8_LAS unsigned*)(lds + (bufoff) + ldsw + _i * 8192), 16, 0, 0); } while (0)
; #define PG8_MMA(ai, bj, At, Bt) do { __builtin_amdgcn_s_setprio(1); _Pragma("unroll") for (int m = 0; m < 4; ++m) _Pragma("unroll") for (int n = 0; n < 2; ++n) _Pragma("unroll") for (int k = 0; k < 2; ++k) \
;     acc[ai][bj][m][n] = __builtin_amdgcn_mfma_f32_16x16x32_bf16(Bt[n][k], At[m][k], acc[ai][bj][m][n], 0, 0, 0); __builtin_amdgcn_s_setprio(0); } while (0)
; #define PG8_WAIT_V(n) asm volatile("s_waitcnt vmcnt(" #n ")" ::: "memory")
; #define PG8_WAIT_L(n) asm volatile("s_waitcnt lgkmcnt(" #n ")" ::: "memory")
; #define PG8_BAR __builtin_amdgcn_s_barrier()
; #define PG8_SCHED __builtin_amdgcn_sched_barrier(0)
; template <class Epi>
; DI void gemm_phase(PG8_LAS unsigned char* lds, const Gemm g, const StaticOrder& S, const Epi& E) {
;     ...
;       PG8_BAR; PG8_WAIT_L(0); PG8_MMA(1, 0, At, B0); PG8_BAR; PG8_SCHED;
;       PG8_STAGE(PG8_SB(1, 1), b3 + hstepB, voffB);
;       PG8_WAIT_V(6); PG8_BAR; PG8_MMA(1, 1, At, B1); PG8_BAR;
;     }
;   DI void operator()(const f32x4 (&acc)[2][2][4][2], const Unit& u, int wr, int wc, int fr, int fq) const {
; #pragma unroll
;     for (int ai = 0; ai < 2; ++ai)
; #pragma unroll
;       for (int m = 0; m < 4; ++m) {
;         const int tok = 256 * u.pm + 128 * ai + 64 * wr + 16 * m + fr;
;         bf16_t* rowp = O + (size_t)(tok >> 8) * ((size_t)ldc * 256) + (size_t)(4 * u.pn + wc) * (256 * 64) + (size_t)(tok & 255) * 64 + 8 * fq;
;         const float rsx = rstd[tok];
; #pragma unroll
;         for (int bj = 0; bj < 2; ++bj) {
;           f32x4 a = acc[ai][bj][m][0], b = acc[ai][bj][m][1];
; #pragma unroll
;           for (int j = 0; j < 4; ++j) { a[j] = fmaxf(a[j], 0.f) * rsx; a[j] *= a[j]; b[j] = fmaxf(b[j], 0.f) * rsx; b[j] *= b[j]; }
;           u32x4 w;
;           w.x = pk_bf16(a[0], a[1]); w.y = pk_bf16(a[2], a[3]); w.z = pk_bf16(b[0], b[1]); w.w = pk_bf16(b[2], b[3]);
;           *(u32x4*)(rowp + 32 * bj) = w;
;         }
;       }
	s_waitcnt lgkmcnt(0)
	s_setprio 1
	s_waitcnt lgkmcnt(0)
	v_mfma_f32_16x16x32_bf16 v[62:65], v[150:153], v[168:171], v[62:65]
	v_mfma_f32_16x16x32_bf16 v[58:61], v[158:161], v[168:171], v[58:61]
	v_mfma_f32_16x16x32_bf16 v[46:49], v[150:153], v[176:179], v[46:49]
	v_mfma_f32_16x16x32_bf16 v[42:45], v[158:161], v[176:179], v[42:45]
	v_mfma_f32_16x16x32_bf16 v[30:33], v[150:153], v[184:187], v[30:33]
	v_mfma_f32_16x16x32_bf16 v[26:29], v[158:161], v[184:187], v[26:29]
	v_mfma_f32_16x16x32_bf16 v[14:17], v[150:153], v[192:195], v[14:17]
	v_mfma_f32_16x16x32_bf16 v[10:13], v[158:161], v[192:195], v[10:13]
	v_mfma_f32_16x16x32_bf16 v[62:65], v[154:157], v[172:175], v[62:65]
	v_mfma_f32_16x16x32_bf16 v[58:61], v[162:165], v[172:175], v[58:61]
	v_mfma_f32_16x16x32_bf16 v[46:49], v[154:157], v[180:183], v[46:49]
	v_mfma_f32_16x16x32_bf16 v[42:45], v[162:165], v[180:183], v[42:45]
	v_mfma_f32_16x16x32_bf16 v[30:33], v[154:157], v[188:191], v[30:33]
	v_mfma_f32_16x16x32_bf16 v[26:29], v[162:165], v[188:191], v[26:29]
	v_mfma_f32_16x16x32_bf16 v[14:17], v[154:157], v[196:199], v[14:17]
	v_mfma_f32_16x16x32_bf16 v[10:13], v[162:165], v[196:199], v[10:13]
	s_setprio 0
	s_barrier
	s_add_u32 s10, s10, 0x10080
	s_addc_u32 s11, s11, 0
	s_add_i32 s28, s28, s36
	v_lshl_add_u64 v[144:145], s[10:11], 0, v[132:133]
	s_mov_b32 m0, s28
	s_nop 0
	global_load_lds_dwordx4 v[144:145], off
	v_lshl_add_u64 v[144:145], s[10:11], 0, v[136:137]
	s_add_i32 m0, s28, 0x2000
	s_nop 0
	global_load_lds_dwordx4 v[144:145], off
	s_waitcnt vmcnt(6)
	s_barrier
	s_setprio 1
	v_mfma_f32_16x16x32_bf16 v[54:57], v[200:203], v[168:171], v[54:57]
	v_mfma_f32_16x16x32_bf16 v[50:53], v[208:211], v[168:171], v[50:53]
	v_mfma_f32_16x16x32_bf16 v[38:41], v[200:203], v[176:179], v[38:41]
	v_mfma_f32_16x16x32_bf16 v[34:37], v[208:211], v[176:179], v[34:37]
	v_mfma_f32_16x16x32_bf16 v[22:25], v[200:203], v[184:187], v[22:25]
	v_mfma_f32_16x16x32_bf16 v[18:21], v[208:211], v[184:187], v[18:21]
	v_mfma_f32_16x16x32_bf16 v[6:9], v[200:203], v[192:195], v[6:9]
	v_mfma_f32_16x16x32_bf16 v[2:5], v[208:211], v[192:195], v[2:5]
	v_mfma_f32_16x16x32_bf16 v[54:57], v[204:207], v[172:175], v[54:57]
	v_mfma_f32_16x16x32_bf16 v[50:53], v[212:215], v[172:175], v[50:53]
	v_mfma_f32_16x16x32_bf16 v[38:41], v[204:207], v[180:183], v[38:41]
	v_mfma_f32_16x16x32_bf16 v[34:37], v[212:215], v[180:183], v[34:37]
	v_mfma_f32_16x16x32_bf16 v[22:25], v[204:207], v[188:191], v[22:25]
	v_mfma_f32_16x16x32_bf16 v[18:21], v[212:215], v[188:191], v[18:21]
	v_mfma_f32_16x16x32_bf16 v[6:9], v[204:207], v[196:199], v[6:9]
	v_mfma_f32_16x16x32_bf16 v[2:5], v[212:215], v[196:199], v[2:5]
	s_setprio 0
	s_add_i32 s54, s54, 2
	s_add_u32 s8, s8, 0x100
	s_addc_u32 s9, s9, 0
	s_add_u32 s52, s52, 0x100
	s_addc_u32 s53, s53, 0
	s_cmp_gt_u32 s54, 13
	s_barrier
	s_cbranch_scc0 .LBB0_69
	s_lshl_b32 s1, s49, 8
	s_add_i32 s1, s1, s43
	v_or_b32_e32 v144, s1, v146
	v_readlane_b32 s28, v254, 44
	v_ashrrev_i32_e32 v145, 31, v144
	v_readlane_b32 s29, v254, 45
	s_lshl_b32 s3, s48, 2
	s_or_b32 s8, s3, s42
	v_lshl_add_u64 v[150:151], v[144:145], 2, s[28:29]
	global_load_dword v168, v[150:151], off
	global_load_dword v170, v[150:151], off offset:64
	global_load_dword v172, v[150:151], off offset:128
	global_load_dword v174, v[150:151], off offset:192
	global_load_dword v176, v[150:151], off offset:512
	global_load_dword v178, v[150:151], off offset:576
	global_load_dword v180, v[150:151], off offset:640
	global_load_dword v182, v[150:151], off offset:704
	s_ashr_i32 s10, s1, 8
	s_ashr_i32 s9, s8, 31
	s_ashr_i32 s11, s10, 31
	s_lshl_b64 s[8:9], s[8:9], 15
	s_lshl_b64 s[10:11], s[10:11], 21
	s_add_u32 s3, s90, s10
	v_max_f32_e32 v0, v126, v126
	v_max_f32_e32 v122, v122, v122
	v_max_f32_e32 v126, v127, v127
	v_max_f32_e32 v123, v123, v123
	v_max_f32_e32 v127, v128, v128
	v_max_f32_e32 v124, v124, v124
	v_max_f32_e32 v128, v129, v129
	v_max_f32_e32 v125, v125, v125
	s_addc_u32 s11, s91, s11
	v_max_f32_e32 v129, v118, v118
	v_max_f32_e32 v145, v114, v114
	v_max_f32_e32 v149, v119, v119
	v_max_f32_e32 v151, v115, v115
	v_max_f32_e32 v152, v120, v120
	v_max_f32_e32 v153, v116, v116
	v_max_f32_e32 v154, v121, v121
	v_max_f32_e32 v155, v117, v117
	v_max_f32_e32 v114, 0, v0
	v_max_f32_e32 v116, 0, v122
	v_max_f32_e32 v115, 0, v126
	v_max_f32_e32 v117, 0, v123
	v_max_f32_e32 v118, 0, v127
	v_max_f32_e32 v120, 0, v124
	v_max_f32_e32 v119, 0, v128
	v_max_f32_e32 v121, 0, v125
	v_lshlrev_b32_e32 v0, 7, v144
	s_add_u32 s10, s3, s8
	v_max_f32_e32 v122, 0, v129
	v_max_f32_e32 v124, 0, v145
	v_max_f32_e32 v123, 0, v149
	v_max_f32_e32 v125, 0, v151
	v_max_f32_e32 v126, 0, v152
	v_max_f32_e32 v128, 0, v153
	v_max_f32_e32 v127, 0, v154
	v_max_f32_e32 v129, 0, v155
	v_and_b32_e32 v0, 0x6780, v0
	s_addc_u32 s11, s11, s9
	v_mov_b32_e32 v143, v1
	v_or_b32_e32 v152, 16, v144
	v_lshl_add_u64 v[156:157], s[10:11], 0, v[0:1]
	v_ashrrev_i32_e32 v153, 31, v152
	v_lshl_add_u64 v[156:157], v[156:157], 0, v[142:143]
	v_lshl_add_u64 v[154:155], v[152:153], 2, s[28:29]
	v_max_f32_e32 v0, v110, v110
	v_max_f32_e32 v106, v106, v106
	v_max_f32_e32 v110, v111, v111
	v_max_f32_e32 v107, v107, v107
	v_max_f32_e32 v111, v112, v112
	v_max_f32_e32 v108, v108, v108
	v_max_f32_e32 v112, v113, v113
	v_max_f32_e32 v109, v109, v109
	v_max_f32_e32 v113, v102, v102
	v_max_f32_e32 v102, 0, v111
	v_max_f32_e32 v90, v90, v90
	v_max_f32_e32 v91, v91, v91
	v_max_f32_e32 v92, v92, v92
	v_max_f32_e32 v93, v93, v93
	v_max_f32_e32 v74, v74, v74
	v_max_f32_e32 v75, v75, v75
	v_max_f32_e32 v76, v76, v76
	v_max_f32_e32 v77, v77, v77
	v_max_f32_e32 v66, v66, v66
	v_max_f32_e32 v67, v67, v67
	s_addk_i32 s1, 0x80
	v_max_f32_e32 v58, v58, v58
	v_max_f32_e32 v59, v59, v59
	v_max_f32_e32 v60, v60, v60
	v_max_f32_e32 v61, v61, v61
	v_max_f32_e32 v42, v42, v42
	v_max_f32_e32 v43, v43, v43
	v_max_f32_e32 v44, v44, v44
	v_max_f32_e32 v45, v45, v45
	v_max_f32_e32 v26, v26, v26
	s_waitcnt vmcnt(7)
;   DI void operator()(const f32x4 (&acc)[2][2][4][2], const Unit& u, int wr, int wc, int fr, int fq) const {
; #pragma unroll
;     for (int ai = 0; ai < 2; ++ai)
; #pragma unroll
;       for (int m = 0; m < 4; ++m) {
;         const int tok = 256 * u.pm + 128 * ai + 64 * wr + 16 * m + fr;
;         bf16_t* rowp = O + (size_t)(tok >> 8) * ((size_t)ldc * 256) + (size_t)(4 * u.pn + wc) * (256 * 64) + (size_t)(tok & 255) * 64 + 8 * fq;
;         const float rsx = rstd[tok];
; #pragma unroll
;         for (int bj = 0; bj < 2; ++bj) {
;           f32x4 a = acc[ai][bj][m][0], b = acc[ai][bj][m][1];
; #pragma unroll
;           for (int j = 0; j < 4; ++j) { a[j] = fmaxf(a[j], 0.f) * rsx; a[j] *= a[j]; b[j] = fmaxf(b[j], 0.f) * rsx; b[j] *= b[j]; }
;           u32x4 w;
;           w.x = pk_bf16(a[0], a[1]); w.y = pk_bf16(a[2], a[3]); w.z = pk_bf16(b[0], b[1]); w.w = pk_bf16(b[2], b[3]);
;           *(u32x4*)(rowp + 32 * bj) = w;
;         }
;       }
	v_pk_mul_f32 v[114:115], v[114:115], v[168:169] op_sel_hi:[1,0]
	v_pk_mul_f32 v[116:117], v[116:117], v[168:169] op_sel_hi:[1,0]
	v_pk_mul_f32 v[118:119], v[118:119], v[168:169] op_sel_hi:[1,0]
	v_pk_mul_f32 v[120:121], v[120:121], v[168:169] op_sel_hi:[1,0]
	v_pk_mul_f32 v[122:123], v[122:123], v[168:169] op_sel_hi:[1,0]
	v_pk_mul_f32 v[124:125], v[124:125], v[168:169] op_sel_hi:[1,0]
	v_pk_mul_f32 v[126:127], v[126:127], v[168:169] op_sel_hi:[1,0]
	v_pk_mul_f32 v[128:129], v[128:129], v[168:169] op_sel_hi:[1,0]
	v_pk_mul_f32 v[114:115], v[114:115], v[114:115]
	v_pk_mul_f32 v[116:117], v[116:117], v[116:117]
	v_pk_mul_f32 v[118:119], v[118:119], v[118:119]
	v_pk_mul_f32 v[120:121], v[120:121], v[120:121]
	v_pk_mul_f32 v[122:123], v[122:123], v[122:123]
	v_pk_mul_f32 v[124:125], v[124:125], v[124:125]
	v_pk_mul_f32 v[126:127], v[126:127], v[126:127]
	v_pk_mul_f32 v[128:129], v[128:129], v[128:129]
	v_cvt_pk_bf16_f32 v114, v114, v115
	v_cvt_pk_bf16_f32 v115, v118, v119
	v_cvt_pk_bf16_f32 v116, v116, v117
	v_cvt_pk_bf16_f32 v117, v120, v121
	v_cvt_pk_bf16_f32 v118, v122, v123
	v_cvt_pk_bf16_f32 v119, v126, v127
	v_cvt_pk_bf16_f32 v120, v124, v125
	v_cvt_pk_bf16_f32 v121, v128, v129
	global_store_dwordx4 v[156:157], v[114:117], off
	global_store_dwordx4 v[156:157], v[118:121], off offset:64
	s_nop 0
	v_max_f32_e32 v115, v98, v98
	v_max_f32_e32 v116, v103, v103
	v_max_f32_e32 v117, v99, v99
	v_max_f32_e32 v118, v104, v104
	v_max_f32_e32 v119, v100, v100
	v_max_f32_e32 v120, v105, v105
	v_max_f32_e32 v121, v101, v101
	v_max_f32_e32 v98, 0, v0
	v_max_f32_e32 v100, 0, v106
	v_max_f32_e32 v99, 0, v110
	v_max_f32_e32 v101, 0, v107
	v_max_f32_e32 v104, 0, v108
	v_max_f32_e32 v103, 0, v112
	v_max_f32_e32 v105, 0, v109
	v_lshlrev_b32_e32 v0, 7, v152
	v_max_f32_e32 v106, 0, v113
	v_max_f32_e32 v108, 0, v115
	v_max_f32_e32 v107, 0, v116
	v_max_f32_e32 v109, 0, v117
	v_max_f32_e32 v110, 0, v118
	v_max_f32_e32 v112, 0, v119
	v_max_f32_e32 v111, 0, v120
	v_max_f32_e32 v113, 0, v121
	v_and_b32_e32 v0, 0x6f80, v0
	v_or_b32_e32 v116, 32, v144
	v_lshl_add_u64 v[120:121], s[10:11], 0, v[0:1]
	v_ashrrev_i32_e32 v117, 31, v116
	v_lshl_add_u64 v[120:121], v[120:121], 0, v[142:143]
	v_lshl_add_u64 v[118:119], v[116:117], 2, s[28:29]
	v_max_f32_e32 v0, v94, v94
	v_max_f32_e32 v94, v95, v95
	v_max_f32_e32 v95, v96, v96
	v_max_f32_e32 v96, v97, v97
	v_max_f32_e32 v97, v86, v86
	v_max_f32_e32 v86, 0, v95
	v_max_f32_e32 v27, v27, v27
	v_max_f32_e32 v28, v28, v28
	v_max_f32_e32 v29, v29, v29
	v_max_f32_e32 v10, v10, v10
	v_max_f32_e32 v11, v11, v11
	v_max_f32_e32 v12, v12, v12
	v_max_f32_e32 v13, v13, v13
	v_readlane_b32 s64, v254, 56
	s_mov_b32 s48, s0
	s_mov_b32 s49, s2
	v_readlane_b32 s65, v254, 57
	s_mov_b32 s54, 0xc2ce8ed0
	s_mov_b32 s55, 0x42b17218
	s_mov_b32 s52, 0x3fb8aa3b
	s_waitcnt vmcnt(8)
	v_pk_mul_f32 v[98:99], v[98:99], v[170:171] op_sel_hi:[1,0]
	v_pk_mul_f32 v[100:101], v[100:101], v[170:171] op_sel_hi:[1,0]
	v_pk_mul_f32 v[102:103], v[102:103], v[170:171] op_sel_hi:[1,0]
	v_pk_mul_f32 v[104:105], v[104:105], v[170:171] op_sel_hi:[1,0]
	v_pk_mul_f32 v[106:107], v[106:107], v[170:171] op_sel_hi:[1,0]
	v_pk_mul_f32 v[108:109], v[108:109], v[170:171] op_sel_hi:[1,0]
	v_pk_mul_f32 v[110:111], v[110:111], v[170:171] op_sel_hi:[1,0]
	v_pk_mul_f32 v[112:113], v[112:113], v[170:171] op_sel_hi:[1,0]
	v_pk_mul_f32 v[98:99], v[98:99], v[98:99]
	v_pk_mul_f32 v[100:101], v[100:101], v[100:101]
	v_pk_mul_f32 v[102:103], v[102:103], v[102:103]
	v_pk_mul_f32 v[104:105], v[104:105], v[104:105]
	v_pk_mul_f32 v[106:107], v[106:107], v[106:107]
	v_pk_mul_f32 v[108:109], v[108:109], v[108:109]
	v_pk_mul_f32 v[110:111], v[110:111], v[110:111]
	v_pk_mul_f32 v[112:113], v[112:113], v[112:113]
	v_cvt_pk_bf16_f32 v98, v98, v99
	v_cvt_pk_bf16_f32 v99, v102, v103
	v_cvt_pk_bf16_f32 v100, v100, v101
	v_cvt_pk_bf16_f32 v101, v104, v105
	v_cvt_pk_bf16_f32 v102, v106, v107
	v_cvt_pk_bf16_f32 v103, v110, v111
	v_cvt_pk_bf16_f32 v104, v108, v109
	v_cvt_pk_bf16_f32 v105, v112, v113
	global_store_dwordx4 v[120:121], v[98:101], off
	global_store_dwordx4 v[120:121], v[102:105], off offset:64
	s_nop 0
	v_max_f32_e32 v99, v82, v82
	v_max_f32_e32 v100, v87, v87
	v_max_f32_e32 v101, v83, v83
	v_max_f32_e32 v102, v88, v88
	v_max_f32_e32 v103, v84, v84
	v_max_f32_e32 v104, v89, v89
	v_max_f32_e32 v105, v85, v85
	v_max_f32_e32 v82, 0, v0
	v_max_f32_e32 v84, 0, v90
	v_max_f32_e32 v83, 0, v94
	v_max_f32_e32 v85, 0, v91
	v_max_f32_e32 v88, 0, v92
	v_max_f32_e32 v87, 0, v96
	v_max_f32_e32 v89, 0, v93
	v_lshlrev_b32_e32 v0, 7, v116
	v_max_f32_e32 v90, 0, v97
	v_max_f32_e32 v92, 0, v99
	v_max_f32_e32 v91, 0, v100
	v_max_f32_e32 v93, 0, v101
	v_max_f32_e32 v94, 0, v102
	v_max_f32_e32 v96, 0, v103
	v_max_f32_e32 v95, 0, v104
	v_max_f32_e32 v97, 0, v105
	v_and_b32_e32 v0, 0x7780, v0
	v_or_b32_e32 v100, 48, v144
	v_lshl_add_u64 v[104:105], s[10:11], 0, v[0:1]
	v_ashrrev_i32_e32 v101, 31, v100
	v_lshl_add_u64 v[104:105], v[104:105], 0, v[142:143]
	v_lshl_add_u64 v[102:103], v[100:101], 2, s[28:29]
	v_max_f32_e32 v0, v78, v78
	v_max_f32_e32 v78, v79, v79
	v_max_f32_e32 v79, v80, v80
	v_max_f32_e32 v80, v81, v81
	v_max_f32_e32 v81, v70, v70
	v_max_f32_e32 v70, 0, v74
	v_max_f32_e32 v74, 0, v76
	v_max_f32_e32 v76, 0, v81
	s_waitcnt vmcnt(9)
;   DI void operator()(const f32x4 (&acc)[2][2][4][2], const Unit& u, int wr, int wc, int fr, int fq) const {
; #pragma unroll
;     for (int ai = 0; ai < 2; ++ai)
; #pragma unroll
;       for (int m = 0; m < 4; ++m) {
;         const int tok = 256 * u.pm + 128 * ai + 64 * wr + 16 * m + fr;
;         bf16_t* rowp = O + (size_t)(tok >> 8) * ((size_t)ldc * 256) + (size_t)(4 * u.pn + wc) * (256 * 64) + (size_t)(tok & 255) * 64 + 8 * fq;
;         const float rsx = rstd[tok];
; #pragma unroll
;         for (int bj = 0; bj < 2; ++bj) {
;           f32x4 a = acc[ai][bj][m][0], b = acc[ai][bj][m][1];
; #pragma unroll
;           for (int j = 0; j < 4; ++j) { a[j] = fmaxf(a[j], 0.f) * rsx; a[j] *= a[j]; b[j] = fmaxf(b[j], 0.f) * rsx; b[j] *= b[j]; }
;           u32x4 w;
;           w.x = pk_bf16(a[0], a[1]); w.y = pk_bf16(a[2], a[3]); w.z = pk_bf16(b[0], b[1]); w.w = pk_bf16(b[2], b[3]);
;           *(u32x4*)(rowp + 32 * bj) = w;
;         }
;       }
	v_pk_mul_f32 v[82:83], v[82:83], v[172:173] op_sel_hi:[1,0]
	v_pk_mul_f32 v[84:85], v[84:85], v[172:173] op_sel_hi:[1,0]
	v_pk_mul_f32 v[86:87], v[86:87], v[172:173] op_sel_hi:[1,0]
	v_pk_mul_f32 v[88:89], v[88:89], v[172:173] op_sel_hi:[1,0]
	v_pk_mul_f32 v[90:91], v[90:91], v[172:173] op_sel_hi:[1,0]
	v_pk_mul_f32 v[92:93], v[92:93], v[172:173] op_sel_hi:[1,0]
	v_pk_mul_f32 v[94:95], v[94:95], v[172:173] op_sel_hi:[1,0]
	v_pk_mul_f32 v[96:97], v[96:97], v[172:173] op_sel_hi:[1,0]
	v_pk_mul_f32 v[82:83], v[82:83], v[82:83]
	v_pk_mul_f32 v[84:85], v[84:85], v[84:85]
	v_pk_mul_f32 v[86:87], v[86:87], v[86:87]
	v_pk_mul_f32 v[88:89], v[88:89], v[88:89]
	v_pk_mul_f32 v[90:91], v[90:91], v[90:91]
	v_pk_mul_f32 v[92:93], v[92:93], v[92:93]
	v_pk_mul_f32 v[94:95], v[94:95], v[94:95]
	v_pk_mul_f32 v[96:97], v[96:97], v[96:97]
	v_cvt_pk_bf16_f32 v82, v82, v83
	v_cvt_pk_bf16_f32 v83, v86, v87
	v_cvt_pk_bf16_f32 v84, v84, v85
	v_cvt_pk_bf16_f32 v85, v88, v89
	v_cvt_pk_bf16_f32 v86, v90, v91
	v_cvt_pk_bf16_f32 v87, v94, v95
	v_cvt_pk_bf16_f32 v88, v92, v93
	v_cvt_pk_bf16_f32 v89, v96, v97
	global_store_dwordx4 v[104:105], v[82:85], off
	global_store_dwordx4 v[104:105], v[86:89], off offset:64
	s_nop 0
	v_max_f32_e32 v83, v71, v71
	v_max_f32_e32 v84, v72, v72
	v_max_f32_e32 v85, v68, v68
	v_max_f32_e32 v86, v73, v73
	v_max_f32_e32 v87, v69, v69
	v_max_f32_e32 v68, 0, v0
	v_max_f32_e32 v69, 0, v78
	v_max_f32_e32 v71, 0, v75
	v_max_f32_e32 v72, 0, v79
	v_max_f32_e32 v73, 0, v80
	v_max_f32_e32 v75, 0, v77
	v_lshlrev_b32_e32 v0, 7, v100
	v_max_f32_e32 v78, 0, v66
	v_max_f32_e32 v77, 0, v83
	v_max_f32_e32 v79, 0, v67
	v_max_f32_e32 v80, 0, v84
	v_max_f32_e32 v84, 0, v85
	v_max_f32_e32 v81, 0, v86
	v_max_f32_e32 v85, 0, v87
	v_and_b32_e32 v0, 0x7f80, v0
	v_or_b32_e32 v66, s1, v146
	v_lshl_add_u64 v[88:89], s[10:11], 0, v[0:1]
	v_ashrrev_i32_e32 v67, 31, v66
	v_lshl_add_u64 v[88:89], v[88:89], 0, v[142:143]
	v_lshl_add_u64 v[86:87], v[66:67], 2, s[28:29]
	s_ashr_i32 s10, s1, 8
	s_ashr_i32 s11, s10, 31
	s_lshl_b64 s[10:11], s[10:11], 21
	s_add_u32 s1, s90, s10
	v_max_f32_e32 v0, v62, v62
	v_max_f32_e32 v62, v63, v63
	v_max_f32_e32 v63, v64, v64
	v_max_f32_e32 v64, v65, v65
	s_addc_u32 s3, s91, s11
	v_max_f32_e32 v65, v54, v54
	v_max_f32_e32 v67, v50, v50
	v_max_f32_e32 v50, 0, v0
	v_max_f32_e32 v54, 0, v63
	v_lshlrev_b32_e32 v0, 7, v66
	s_add_u32 s8, s1, s8
	v_and_b32_e32 v0, 0x6780, v0
	s_addc_u32 s9, s3, s9
	s_mov_b64 s[10:11], s[6:7]
	s_cmp_eq_u32 s47, s59
	s_waitcnt vmcnt(10)
	v_pk_mul_f32 v[68:69], v[68:69], v[174:175] op_sel_hi:[1,0]
	v_pk_mul_f32 v[70:71], v[70:71], v[174:175] op_sel_hi:[1,0]
	v_pk_mul_f32 v[72:73], v[72:73], v[174:175] op_sel_hi:[1,0]
	v_pk_mul_f32 v[74:75], v[74:75], v[174:175] op_sel_hi:[1,0]
	v_pk_mul_f32 v[76:77], v[76:77], v[174:175] op_sel_hi:[1,0]
	v_pk_mul_f32 v[78:79], v[78:79], v[174:175] op_sel_hi:[1,0]
	v_pk_mul_f32 v[80:81], v[80:81], v[174:175] op_sel_hi:[1,0]
	v_pk_mul_f32 v[82:83], v[84:85], v[174:175] op_sel_hi:[1,0]
	v_pk_mul_f32 v[68:69], v[68:69], v[68:69]
	v_pk_mul_f32 v[70:71], v[70:71], v[70:71]
	v_pk_mul_f32 v[72:73], v[72:73], v[72:73]
	v_pk_mul_f32 v[74:75], v[74:75], v[74:75]
	v_pk_mul_f32 v[76:77], v[76:77], v[76:77]
	v_pk_mul_f32 v[78:79], v[78:79], v[78:79]
	v_pk_mul_f32 v[80:81], v[80:81], v[80:81]
	v_pk_mul_f32 v[82:83], v[82:83], v[82:83]
	v_cvt_pk_bf16_f32 v68, v68, v69
	v_cvt_pk_bf16_f32 v69, v72, v73
	v_cvt_pk_bf16_f32 v70, v70, v71
	v_cvt_pk_bf16_f32 v71, v74, v75
	v_cvt_pk_bf16_f32 v72, v76, v77
	v_cvt_pk_bf16_f32 v73, v80, v81
	v_cvt_pk_bf16_f32 v74, v78, v79
	v_cvt_pk_bf16_f32 v75, v82, v83
	global_store_dwordx4 v[88:89], v[68:71], off
	global_store_dwordx4 v[88:89], v[72:75], off offset:64
	s_nop 0
	v_max_f32_e32 v69, v55, v55
	v_max_f32_e32 v70, v51, v51
	v_max_f32_e32 v71, v56, v56
	v_max_f32_e32 v72, v52, v52
	v_max_f32_e32 v73, v57, v57
	v_max_f32_e32 v74, v53, v53
	v_max_f32_e32 v52, 0, v58
	v_max_f32_e32 v51, 0, v62
	v_max_f32_e32 v53, 0, v59
	v_max_f32_e32 v56, 0, v60
	v_max_f32_e32 v55, 0, v64
	v_max_f32_e32 v57, 0, v61
	v_max_f32_e32 v58, 0, v65
	v_max_f32_e32 v60, 0, v67
	v_max_f32_e32 v59, 0, v69
	v_max_f32_e32 v61, 0, v70
	v_max_f32_e32 v62, 0, v71
	v_max_f32_e32 v64, 0, v72
	v_max_f32_e32 v63, 0, v73
	v_max_f32_e32 v65, 0, v74
	v_or_b32_e32 v70, 16, v66
	v_lshl_add_u64 v[74:75], s[8:9], 0, v[0:1]
	v_ashrrev_i32_e32 v71, 31, v70
	v_lshl_add_u64 v[74:75], v[74:75], 0, v[142:143]
	v_lshl_add_u64 v[72:73], v[70:71], 2, s[28:29]
	v_max_f32_e32 v0, v46, v46
	v_max_f32_e32 v46, v47, v47
	v_max_f32_e32 v47, v48, v48
	v_max_f32_e32 v48, v49, v49
	v_max_f32_e32 v49, v38, v38
	v_max_f32_e32 v38, 0, v47
	s_waitcnt vmcnt(11)
;   DI void operator()(const f32x4 (&acc)[2][2][4][2], const Unit& u, int wr, int wc, int fr, int fq) const {
; #pragma unroll
;     for (int ai = 0; ai < 2; ++ai)
; #pragma unroll
;       for (int m = 0; m < 4; ++m) {
;         const int tok = 256 * u.pm + 128 * ai + 64 * wr + 16 * m + fr;
;         bf16_t* rowp = O + (size_t)(tok >> 8) * ((size_t)ldc * 256) + (size_t)(4 * u.pn + wc) * (256 * 64) + (size_t)(tok & 255) * 64 + 8 * fq;
;         const float rsx = rstd[tok];
; #pragma unroll
;         for (int bj = 0; bj < 2; ++bj) {
;           f32x4 a = acc[ai][bj][m][0], b = acc[ai][bj][m][1];
; #pragma unroll
;           for (int j = 0; j < 4; ++j) { a[j] = fmaxf(a[j], 0.f) * rsx; a[j] *= a[j]; b[j] = fmaxf(b[j], 0.f) * rsx; b[j] *= b[j]; }
;           u32x4 w;
;           w.x = pk_bf16(a[0], a[1]); w.y = pk_bf16(a[2], a[3]); w.z = pk_bf16(b[0], b[1]); w.w = pk_bf16(b[2], b[3]);
;           *(u32x4*)(rowp + 32 * bj) = w;
;         }
;       }
	v_pk_mul_f32 v[50:51], v[50:51], v[176:177] op_sel_hi:[1,0]
	v_pk_mul_f32 v[52:53], v[52:53], v[176:177] op_sel_hi:[1,0]
	v_pk_mul_f32 v[54:55], v[54:55], v[176:177] op_sel_hi:[1,0]
	v_pk_mul_f32 v[56:57], v[56:57], v[176:177] op_sel_hi:[1,0]
	v_pk_mul_f32 v[58:59], v[58:59], v[176:177] op_sel_hi:[1,0]
	v_pk_mul_f32 v[60:61], v[60:61], v[176:177] op_sel_hi:[1,0]
	v_pk_mul_f32 v[62:63], v[62:63], v[176:177] op_sel_hi:[1,0]
	v_pk_mul_f32 v[64:65], v[64:65], v[176:177] op_sel_hi:[1,0]
	v_pk_mul_f32 v[50:51], v[50:51], v[50:51]
	v_pk_mul_f32 v[52:53], v[52:53], v[52:53]
	v_pk_mul_f32 v[54:55], v[54:55], v[54:55]
	v_pk_mul_f32 v[56:57], v[56:57], v[56:57]
	v_pk_mul_f32 v[58:59], v[58:59], v[58:59]
	v_pk_mul_f32 v[60:61], v[60:61], v[60:61]
	v_pk_mul_f32 v[62:63], v[62:63], v[62:63]
	v_pk_mul_f32 v[64:65], v[64:65], v[64:65]
	v_cvt_pk_bf16_f32 v50, v50, v51
	v_cvt_pk_bf16_f32 v51, v54, v55
	v_cvt_pk_bf16_f32 v52, v52, v53
	v_cvt_pk_bf16_f32 v53, v56, v57
	v_cvt_pk_bf16_f32 v54, v58, v59
	v_cvt_pk_bf16_f32 v55, v62, v63
	v_cvt_pk_bf16_f32 v56, v60, v61
	v_cvt_pk_bf16_f32 v57, v64, v65
	global_store_dwordx4 v[74:75], v[50:53], off
	global_store_dwordx4 v[74:75], v[54:57], off offset:64
	s_nop 0
	v_max_f32_e32 v51, v34, v34
	v_max_f32_e32 v52, v39, v39
	v_max_f32_e32 v53, v35, v35
	v_max_f32_e32 v54, v40, v40
	v_max_f32_e32 v55, v36, v36
	v_max_f32_e32 v56, v41, v41
	v_max_f32_e32 v57, v37, v37
	v_max_f32_e32 v34, 0, v0
	v_max_f32_e32 v36, 0, v42
	v_max_f32_e32 v35, 0, v46
	v_max_f32_e32 v37, 0, v43
	v_max_f32_e32 v40, 0, v44
	v_max_f32_e32 v39, 0, v48
	v_max_f32_e32 v41, 0, v45
	v_lshlrev_b32_e32 v0, 7, v70
	v_max_f32_e32 v42, 0, v49
	v_max_f32_e32 v44, 0, v51
	v_max_f32_e32 v43, 0, v52
	v_max_f32_e32 v45, 0, v53
	v_max_f32_e32 v46, 0, v54
	v_max_f32_e32 v48, 0, v55
	v_max_f32_e32 v47, 0, v56
	v_max_f32_e32 v49, 0, v57
	v_and_b32_e32 v0, 0x7f80, v0
	v_or_b32_e32 v52, 32, v66
	v_lshl_add_u64 v[56:57], s[8:9], 0, v[0:1]
	v_ashrrev_i32_e32 v53, 31, v52
	v_lshl_add_u64 v[56:57], v[56:57], 0, v[142:143]
	v_lshl_add_u64 v[54:55], v[52:53], 2, s[28:29]
	v_max_f32_e32 v0, v30, v30
	v_max_f32_e32 v30, v31, v31
	v_max_f32_e32 v31, v32, v32
	v_max_f32_e32 v32, v33, v33
	v_max_f32_e32 v33, v22, v22
	v_max_f32_e32 v22, 0, v31
	s_waitcnt vmcnt(12)
	v_pk_mul_f32 v[34:35], v[34:35], v[178:179] op_sel_hi:[1,0]
	v_pk_mul_f32 v[36:37], v[36:37], v[178:179] op_sel_hi:[1,0]
	v_pk_mul_f32 v[38:39], v[38:39], v[178:179] op_sel_hi:[1,0]
	v_pk_mul_f32 v[40:41], v[40:41], v[178:179] op_sel_hi:[1,0]
	v_pk_mul_f32 v[42:43], v[42:43], v[178:179] op_sel_hi:[1,0]
	v_pk_mul_f32 v[44:45], v[44:45], v[178:179] op_sel_hi:[1,0]
	v_pk_mul_f32 v[46:47], v[46:47], v[178:179] op_sel_hi:[1,0]
	v_pk_mul_f32 v[48:49], v[48:49], v[178:179] op_sel_hi:[1,0]
	v_pk_mul_f32 v[34:35], v[34:35], v[34:35]
	v_pk_mul_f32 v[36:37], v[36:37], v[36:37]
	v_pk_mul_f32 v[38:39], v[38:39], v[38:39]
	v_pk_mul_f32 v[40:41], v[40:41], v[40:41]
	v_pk_mul_f32 v[42:43], v[42:43], v[42:43]
	v_pk_mul_f32 v[44:45], v[44:45], v[44:45]
	v_pk_mul_f32 v[46:47], v[46:47], v[46:47]
	v_pk_mul_f32 v[48:49], v[48:49], v[48:49]
	v_cvt_pk_bf16_f32 v34, v34, v35
	v_cvt_pk_bf16_f32 v35, v38, v39
	v_cvt_pk_bf16_f32 v36, v36, v37
	v_cvt_pk_bf16_f32 v37, v40, v41
	v_cvt_pk_bf16_f32 v38, v42, v43
	v_cvt_pk_bf16_f32 v39, v46, v47
	v_cvt_pk_bf16_f32 v40, v44, v45
	v_cvt_pk_bf16_f32 v41, v48, v49
	global_store_dwordx4 v[56:57], v[34:37], off
	global_store_dwordx4 v[56:57], v[38:41], off offset:64
	s_nop 0
	v_max_f32_e32 v35, v18, v18
	v_max_f32_e32 v36, v23, v23
	v_max_f32_e32 v37, v19, v19
	v_max_f32_e32 v38, v24, v24
	v_max_f32_e32 v39, v20, v20
	v_max_f32_e32 v40, v25, v25
	v_max_f32_e32 v41, v21, v21
	v_max_f32_e32 v18, 0, v0
	v_max_f32_e32 v20, 0, v26
	v_max_f32_e32 v19, 0, v30
	v_max_f32_e32 v21, 0, v27
	v_max_f32_e32 v24, 0, v28
	v_max_f32_e32 v23, 0, v32
	v_max_f32_e32 v25, 0, v29
	v_lshlrev_b32_e32 v0, 7, v52
	v_max_f32_e32 v26, 0, v33
	v_max_f32_e32 v28, 0, v35
	v_max_f32_e32 v27, 0, v36
	v_max_f32_e32 v29, 0, v37
	v_max_f32_e32 v30, 0, v38
	v_max_f32_e32 v32, 0, v39
	v_max_f32_e32 v31, 0, v40
	v_max_f32_e32 v33, 0, v41
	v_and_b32_e32 v0, 0x7f80, v0
	v_or_b32_e32 v36, 48, v66
	v_lshl_add_u64 v[40:41], s[8:9], 0, v[0:1]
	v_ashrrev_i32_e32 v37, 31, v36
	v_lshl_add_u64 v[40:41], v[40:41], 0, v[142:143]
	v_lshl_add_u64 v[38:39], v[36:37], 2, s[28:29]
	v_max_f32_e32 v0, v14, v14
	v_max_f32_e32 v14, v15, v15
	v_max_f32_e32 v15, v16, v16
	v_max_f32_e32 v16, v17, v17
	v_max_f32_e32 v17, v6, v6
	v_max_f32_e32 v6, 0, v15
	s_waitcnt vmcnt(13)
; #define PG8_WAIT_V(n) asm volatile("s_waitcnt vmcnt(" #n ")" ::: "memory")
; #define PG8_BAR __builtin_amdgcn_s_barrier()
; template <class Epi>
; DI void gemm_phase(PG8_LAS unsigned char* lds, const Gemm g, const StaticOrder& S, const Epi& E) {
;     ...
;     E(acc, cur, wr, wc, fr, fq);
;     if (!has_next) break;
; #pragma unroll
;     for (int a = 0; a < 2; ++a)
; #pragma unroll
;       for (int b = 0; b < 2; ++b)
; #pragma unroll
;         for (int m = 0; m < 4; ++m)
; #pragma unroll
;           for (int n = 0; n < 2; ++n) acc[a][b][m][n] = (f32x4){0.f, 0.f, 0.f, 0.f};
;     cur = nxt; cA = nA; cB = nB; ++ui;
;   }
;   PG8_WAIT_V(0);
;   if (wr == 0) PG8_BAR;
;   DI void operator()(const f32x4 (&acc)[2][2][4][2], const Unit& u, int wr, int wc, int fr, int fq) const {
; #pragma unroll
;     for (int ai = 0; ai < 2; ++ai)
; #pragma unroll
;       for (int m = 0; m < 4; ++m) {
;         const int tok = 256 * u.pm + 128 * ai + 64 * wr + 16 * m + fr;
;         bf16_t* rowp = O + (size_t)(tok >> 8) * ((size_t)ldc * 256) + (size_t)(4 * u.pn + wc) * (256 * 64) + (size_t)(tok & 255) * 64 + 8 * fq;
;         const float rsx = rstd[tok];
; #pragma unroll
;         for (int bj = 0; bj < 2; ++bj) {
;           f32x4 a = acc[ai][bj][m][0], b = acc[ai][bj][m][1];
; #pragma unroll
;           for (int j = 0; j < 4; ++j) { a[j] = fmaxf(a[j], 0.f) * rsx; a[j] *= a[j]; b[j] = fmaxf(b[j], 0.f) * rsx; b[j] *= b[j]; }
;           u32x4 w;
;           w.x = pk_bf16(a[0], a[1]); w.y = pk_bf16(a[2], a[3]); w.z = pk_bf16(b[0], b[1]); w.w = pk_bf16(b[2], b[3]);
;           *(u32x4*)(rowp + 32 * bj) = w;
;         }
;       }
	v_pk_mul_f32 v[18:19], v[18:19], v[180:181] op_sel_hi:[1,0]
	v_pk_mul_f32 v[20:21], v[20:21], v[180:181] op_sel_hi:[1,0]
	v_pk_mul_f32 v[22:23], v[22:23], v[180:181] op_sel_hi:[1,0]
	v_pk_mul_f32 v[24:25], v[24:25], v[180:181] op_sel_hi:[1,0]
	v_pk_mul_f32 v[26:27], v[26:27], v[180:181] op_sel_hi:[1,0]
	v_pk_mul_f32 v[28:29], v[28:29], v[180:181] op_sel_hi:[1,0]
	v_pk_mul_f32 v[30:31], v[30:31], v[180:181] op_sel_hi:[1,0]
	v_pk_mul_f32 v[32:33], v[32:33], v[180:181] op_sel_hi:[1,0]
	v_pk_mul_f32 v[18:19], v[18:19], v[18:19]
	v_pk_mul_f32 v[20:21], v[20:21], v[20:21]
	v_pk_mul_f32 v[22:23], v[22:23], v[22:23]
	v_pk_mul_f32 v[24:25], v[24:25], v[24:25]
	v_pk_mul_f32 v[26:27], v[26:27], v[26:27]
	v_pk_mul_f32 v[28:29], v[28:29], v[28:29]
	v_pk_mul_f32 v[30:31], v[30:31], v[30:31]
	v_pk_mul_f32 v[32:33], v[32:33], v[32:33]
	v_cvt_pk_bf16_f32 v18, v18, v19
	v_cvt_pk_bf16_f32 v19, v22, v23
	v_cvt_pk_bf16_f32 v20, v20, v21
	v_cvt_pk_bf16_f32 v21, v24, v25
	v_cvt_pk_bf16_f32 v22, v26, v27
	v_cvt_pk_bf16_f32 v23, v30, v31
	v_cvt_pk_bf16_f32 v24, v28, v29
	v_cvt_pk_bf16_f32 v25, v32, v33
	global_store_dwordx4 v[40:41], v[18:21], off
	global_store_dwordx4 v[40:41], v[22:25], off offset:64
	s_nop 0
	v_max_f32_e32 v19, v2, v2
	v_max_f32_e32 v20, v7, v7
	v_max_f32_e32 v21, v3, v3
	v_max_f32_e32 v22, v8, v8
	v_max_f32_e32 v23, v4, v4
	v_max_f32_e32 v24, v9, v9
	v_max_f32_e32 v25, v5, v5
	v_max_f32_e32 v2, 0, v0
	v_max_f32_e32 v4, 0, v10
	v_max_f32_e32 v3, 0, v14
	v_max_f32_e32 v5, 0, v11
	v_max_f32_e32 v8, 0, v12
	v_max_f32_e32 v7, 0, v16
	v_max_f32_e32 v9, 0, v13
	v_lshlrev_b32_e32 v0, 7, v36
	v_max_f32_e32 v10, 0, v17
	v_max_f32_e32 v12, 0, v19
	v_max_f32_e32 v11, 0, v20
	v_max_f32_e32 v13, 0, v21
	v_max_f32_e32 v14, 0, v22
	v_max_f32_e32 v16, 0, v23
	v_max_f32_e32 v15, 0, v24
	v_max_f32_e32 v17, 0, v25
	v_and_b32_e32 v0, 0x7f80, v0
	v_lshl_add_u64 v[20:21], s[8:9], 0, v[0:1]
	v_lshl_add_u64 v[20:21], v[20:21], 0, v[142:143]
	s_mov_b64 s[8:9], s[4:5]
	s_waitcnt vmcnt(14)
	v_pk_mul_f32 v[2:3], v[2:3], v[182:183] op_sel_hi:[1,0]
	v_pk_mul_f32 v[4:5], v[4:5], v[182:183] op_sel_hi:[1,0]
	v_pk_mul_f32 v[6:7], v[6:7], v[182:183] op_sel_hi:[1,0]
	v_pk_mul_f32 v[8:9], v[8:9], v[182:183] op_sel_hi:[1,0]
	v_pk_mul_f32 v[10:11], v[10:11], v[182:183] op_sel_hi:[1,0]
	v_pk_mul_f32 v[12:13], v[12:13], v[182:183] op_sel_hi:[1,0]
	v_pk_mul_f32 v[14:15], v[14:15], v[182:183] op_sel_hi:[1,0]
	v_pk_mul_f32 v[16:17], v[16:17], v[182:183] op_sel_hi:[1,0]
	v_pk_mul_f32 v[2:3], v[2:3], v[2:3]
	v_pk_mul_f32 v[4:5], v[4:5], v[4:5]
	v_pk_mul_f32 v[6:7], v[6:7], v[6:7]
	v_pk_mul_f32 v[8:9], v[8:9], v[8:9]
	v_pk_mul_f32 v[10:11], v[10:11], v[10:11]
	v_pk_mul_f32 v[12:13], v[12:13], v[12:13]
	v_pk_mul_f32 v[14:15], v[14:15], v[14:15]
	v_pk_mul_f32 v[16:17], v[16:17], v[16:17]
	v_cvt_pk_bf16_f32 v2, v2, v3
	v_cvt_pk_bf16_f32 v3, v6, v7
	v_cvt_pk_bf16_f32 v4, v4, v5
	v_cvt_pk_bf16_f32 v5, v8, v9
	v_cvt_pk_bf16_f32 v6, v10, v11
	v_cvt_pk_bf16_f32 v7, v14, v15
	v_cvt_pk_bf16_f32 v8, v12, v13
	v_cvt_pk_bf16_f32 v9, v16, v17
	global_store_dwordx4 v[20:21], v[2:5], off
	global_store_dwordx4 v[20:21], v[6:9], off offset:64
	s_cbranch_scc0 .LBB0_62
	s_waitcnt vmcnt(0)
	s_cmpk_gt_u32 s30, 0xff
	v_readlane_b32 s48, v254, 60
	s_mov_b32 s49, 0xffff
	s_movk_i32 s43, 0xff
	s_movk_i32 s58, 0x204
	s_cbranch_scc1 .LBB0_73
	s_barrier

; DI float bf_lo(unsigned u) { return __uint_as_float(u << 16); }
; DI float bf_hi(unsigned u) { return __uint_as_float(u & 0xffff0000u); }
; DI int otid() { int t = threadIdx.x; asm volatile("" : "+v"(t)); return t; }
; DI void phase_resid(const float* x_f32, bf16_t* xb, const bf16_t* y, const float* g_post, float* out_f32, float* rstd_out, bool write_xb) {
;   const int lane = otid() & 63;
;   const int gw = blockIdx.x * (NT / 64) + (otid() >> 6), nw = gridDim.x * (NT / 64);
;   for (int row = gw; row < T_TOK; row += nw) {
;     float xv[2][8];
; #pragma unroll
;     for (int j = 0; j < 2; ++j) {
;       const size_t off = (size_t)row * 1024 + j * 512 + lane * 8;
;       if (x_f32) {
;         const float4 a = *(const float4*)(x_f32 + off), c = *(const float4*)(x_f32 + off + 4);
;         xv[j][0] = a.x; xv[j][1] = a.y; xv[j][2] = a.z; xv[j][3] = a.w; xv[j][4] = c.x; xv[j][5] = c.y; xv[j][6] = c.z; xv[j][7] = c.w;
;       } else {
;         const uint4 u = *(const uint4*)(xb + off);
;         xv[j][0] = bf_lo(u.x); xv[j][1] = bf_hi(u.x); xv[j][2] = bf_lo(u.y); xv[j][3] = bf_hi(u.y);
;         xv[j][4] = bf_lo(u.z); xv[j][5] = bf_hi(u.z); xv[j][6] = bf_lo(u.w); xv[j][7] = bf_hi(u.w);
;       }
;     }
;     if (y) {
;       float yv[2][8];
;       float ss = 0.f;
; #pragma unroll
;       for (int j = 0; j < 2; ++j) {
;         const uint4 u = *(const uint4*)(y + (size_t)row * 1024 + j * 512 + lane * 8);
.LBB0_75:
	s_andn2_b64 vcc, exec, s[0:1]
	s_cbranch_vccnz .LBB0_82
	v_mov_b32_e32 v0, v228
	v_mov_b32_e32 v2, v228
	v_readlane_b32 s0, v251, 4
	v_ashrrev_i32_e32 v2, 6, v2
	s_nop 0
	v_add_u32_e32 v2, s0, v2
	s_mov_b32 s0, 0x10000
	v_cmp_gt_i32_e32 vcc, s0, v2
	s_and_saveexec_b64 s[2:3], vcc
	s_cbranch_execz .LBB0_81
	v_readlane_b32 s0, v255, 1
	v_readlane_b32 s1, v255, 2
	s_lshl_b32 s0, s0, 10
	s_ashr_i32 s1, s0, 31
	v_readlane_b32 s48, v253, 59
	s_lshl_b64 s[0:1], s[0:1], 2
	v_readlane_b32 s52, v253, 63
	v_readlane_b32 s53, v254, 0
	s_add_u32 s0, s52, s0
	s_waitcnt lgkmcnt(0)
	v_and_b32_e32 v15, 63, v0
	s_addc_u32 s1, s53, s1
	v_lshlrev_b32_e32 v0, 5, v15
	v_cmp_lt_i32_e32 vcc, v234, v233
	v_lshl_add_u64 v[4:5], s[0:1], 0, v[0:1]
	v_readlane_b32 s62, v254, 9
	v_cndmask_b32_e32 v0, v232, v234, vcc
	v_cmp_lt_i32_e32 vcc, v235, v233
	v_readlane_b32 s63, v254, 10
	v_readlane_b32 s49, v253, 60
	v_cndmask_b32_e32 v3, v232, v235, vcc
	v_lshlrev_b32_e32 v10, 2, v3
	v_xor_b32_e32 v3, 8, v232
	v_cmp_lt_i32_e32 vcc, v3, v233
	v_readlane_b32 s54, v254, 1
	v_readlane_b32 s55, v254, 2
	v_cndmask_b32_e32 v3, v232, v3, vcc
	v_lshlrev_b32_e32 v11, 2, v3
	v_xor_b32_e32 v3, 4, v232
	v_cmp_lt_i32_e32 vcc, v3, v233
	v_readlane_b32 s58, v254, 5
	s_mov_b32 s62, 0x6dc9c883
	v_cndmask_b32_e32 v3, v232, v3, vcc
	v_lshlrev_b32_e32 v12, 2, v3
	v_xor_b32_e32 v3, 2, v232
	v_cmp_lt_i32_e32 vcc, v3, v233
	v_mov_b64_e32 v[6:7], 0x1b10e000
	s_mov_b32 s49, 0xffff
	v_cndmask_b32_e32 v3, v232, v3, vcc
	v_cmp_lt_i32_e32 vcc, v250, v233
	v_lshlrev_b32_e32 v13, 2, v3
	v_readlane_b32 s48, v254, 60
	v_cndmask_b32_e32 v3, v232, v250, vcc
	v_lshlrev_b32_e32 v14, 2, v3
	v_ashrrev_i32_e32 v3, 31, v2
	v_lshlrev_b64 v[8:9], 11, v[2:3]
	s_movk_i32 s58, 0x204
	s_mov_b32 s55, 0x42b17218
	s_mov_b32 s54, 0xc2ce8ed0
	s_mov_b32 s63, 0x3fc45f30
	s_mov_b32 s52, 0x3fb8aa3b
	v_cmp_eq_u32_e64 s[0:1], 0, v15
	v_lshlrev_b32_e32 v0, 2, v0
	v_lshl_add_u64 v[6:7], v[2:3], 2, v[6:7]
	v_lshl_or_b32 v8, v15, 4, v8
	s_mov_b64 s[4:5], 0
	v_readlane_b32 s50, v253, 61
	v_readlane_b32 s51, v253, 62
	v_readlane_b32 s56, v254, 3
	v_readlane_b32 s57, v254, 4
	v_readlane_b32 s59, v254, 6
	v_readlane_b32 s60, v254, 7
	v_readlane_b32 s61, v254, 8
	v_readfirstlane_b32 s0, v2
	global_load_dwordx4 v[100:103], v[4:5], off
	global_load_dwordx4 v[104:107], v[4:5], off offset:16
	global_load_dwordx4 v[108:111], v[4:5], off offset:2048
	global_load_dwordx4 v[112:115], v[4:5], off offset:2064
	s_add_u32 s4, s86, 0xaf0e000
	s_addc_u32 s5, s87, 0
	s_add_u32 s6, s86, 0x2f0e000
	s_addc_u32 s7, s87, 0
	v_and_b32_e32 v93, 63, v228
	v_lshlrev_b32_e32 v95, 5, v93
	v_lshlrev_b32_e32 v93, 4, v93
	v_readlane_b32 s98, v253, 43
	s_mov_b64 exec, -1
	s_lshl_b32 s1, s0, 11
	v_add_u32_e32 v91, s1, v93
	global_load_dwordx4 v[16:19], v91, s[4:5]
	global_load_dwordx4 v[20:23], v91, s[4:5] offset:1024
	global_load_dwordx4 v[24:27], v91, s[6:7]
	global_load_dwordx4 v[28:31], v91, s[6:7] offset:1024
	s_add_u32 s1, s0, s98
	s_min_u32 s1, s1, 0xffff
	s_lshl_b32 s1, s1, 11
	v_add_u32_e32 v91, s1, v93
	global_load_dwordx4 v[32:35], v91, s[4:5]
	global_load_dwordx4 v[36:39], v91, s[4:5] offset:1024
	global_load_dwordx4 v[40:43], v91, s[6:7]
	global_load_dwordx4 v[44:47], v91, s[6:7] offset:1024
	s_mov_b32 s99, 1

; DI float frsq(float x) { return __builtin_amdgcn_rsqf(x); }
; DI void phase_resid(const float* x_f32, bf16_t* xb, const bf16_t* y, const float* g_post, float* out_f32, float* rstd_out, bool write_xb) {
;     ...
;     if (rstd_out) {
;       float ss = 0.f;
; #pragma unroll
;       for (int j = 0; j < 2; ++j)
; #pragma unroll
;         for (int e = 0; e < 8; ++e) ss += xv[j][e] * xv[j][e];
;       ss = wave_sum(ss);
;       if (lane == 0) rstd_out[row] = frsq(ss * (1.f / 1024.f) + EPS);
;     }
;   }
.Lresid_b_done:
	s_waitcnt vmcnt(0)
.LBB0_81:
	s_or_b64 exec, exec, s[2:3]

; #define MFMA(a, b, c) __builtin_amdgcn_mfma_f32_32x32x16_bf16((a), (b), (c), 0, 0, 0)
; DI float fexp2(float x) { return __builtin_amdgcn_exp2f(x); }
; DI float xhalf(float v) { return __shfl_xor(v, 32); }
; template <int NCH, int MODE, bool BOUND> ...
;     ...
;     const char* kb0 = cur + (hf * 64 + r) * KSTR + h * 16;
;     constexpr int NC2 = NCH < 2 ? NCH : 2;
;     bf16x8 ka[NC2][2], kb[NC2][2], kc[2], kd[2];
; #pragma unroll
;     for (int c = 0; c < NC2; ++c)
; #pragma unroll
;       for (int ks = 0; ks < 2; ++ks) {
;         ka[c][ks] = *(const bf16x8*)(kb0 + c * 64 + ks * 32);
;         kb[c][ks] = *(const bf16x8*)(kb0 + 32 * KSTR + c * 64 + ks * 32);
;       }
;     __builtin_amdgcn_sched_barrier(0);
;     if (NCH == 3) {
; #pragma unroll
;       for (int ks = 0; ks < 2; ++ks) {
;         kc[ks] = *(const bf16x8*)(kb0 + 2 * 64 + ks * 32);
;         kd[ks] = *(const bf16x8*)(kb0 + 32 * KSTR + 2 * 64 + ks * 32);
;       }
;     }
; #pragma unroll
;     for (int c = 0; c < NC2; ++c)
; #pragma unroll
;       for (int ks = 0; ks < 2; ++ks) {
;         s0 = MFMA(ka[c][ks], qf[c][ks], s0);
;         s1 = MFMA(kb[c][ks], qf[c][ks], s1);
;       }
;     if (NCH == 3) {
; #pragma unroll
;       for (int ks = 0; ks < 2; ++ks) {
;         s0 = MFMA(kc[ks], qf[NCH - 1][ks], s0);
;         s1 = MFMA(kd[ks], qf[NCH - 1][ks], s1);
;       }
;     }
;     ...
;       float mx = fmaxf(s0[0], s1[0]);
; #pragma unroll
;       for (int i = 1; i < 16; ++i) mx = fmaxf(mx, fmaxf(s0[i], s1[i]));
;       mx = fmaxf(mx, xhalf(mx));
;       const float mnew = fmaxf(m, mx);
;       const float alpha = fexp2(m - mnew);
;       m = mnew;
;       float ps = 0.f;
; #pragma unroll
;       for (int i = 0; i < 16; ++i) {
;         s0[i] = fexp2(s0[i] - mnew);
;         s1[i] = fexp2(s1[i] - mnew);
;         ps += s0[i] + s1[i];
;       }
;       l = l * alpha + ps;
; #pragma unroll
;       for (int i = 0; i < 16; ++i) { o0[i] *= alpha; o1[i] *= alpha; }
;     }
.LBB0_321:
	s_bitcmp1_b32 s50, 0
	s_cselect_b32 s11, 0xac00, 0
	s_add_i32 s11, s11, 0
	v_add3_u32 v154, s11, v99, v0
	ds_read_b128 v[34:37], v154
	ds_read_b128 v[90:93], v154 offset:32
	ds_read_b128 v[38:41], v154 offset:4608
	s_waitcnt vmcnt(0)
	ds_read_b128 v[94:97], v154 offset:4640
	ds_read_b128 v[108:111], v154 offset:64
	ds_read_b128 v[112:115], v154 offset:96
	ds_read_b128 v[116:119], v154 offset:4672
	ds_read_b128 v[120:123], v154 offset:4704
	s_waitcnt lgkmcnt(7)
	v_mfma_f32_32x32x16_bf16 v[50:65], v[34:37], v[74:77], 0
	s_lshl_b64 s[8:9], s[8:9], 1
	v_add3_u32 v153, s11, v105, v0
	s_waitcnt lgkmcnt(5)
	v_mfma_f32_32x32x16_bf16 v[34:49], v[38:41], v[74:77], 0
	v_mfma_f32_32x32x16_bf16 v[50:65], v[90:93], v[78:81], v[50:65]
	v_lshl_add_u64 v[90:91], v[100:101], 0, s[8:9]
	global_load_dwordx4 v[90:93], v[90:91], off
	s_waitcnt lgkmcnt(4)
	v_mfma_f32_32x32x16_bf16 v[34:49], v[94:97], v[78:81], v[34:49]
	v_lshl_add_u64 v[94:95], v[102:103], 0, s[8:9]
	global_load_dwordx4 v[94:97], v[94:95], off
	s_waitcnt lgkmcnt(3)
	v_mfma_f32_32x32x16_bf16 v[50:65], v[108:111], v[82:85], v[50:65]
	s_waitcnt lgkmcnt(1)
	v_mfma_f32_32x32x16_bf16 v[34:49], v[116:119], v[82:85], v[34:49]
	v_mfma_f32_32x32x16_bf16 v[50:65], v[112:115], v[86:89], v[50:65]
	s_waitcnt lgkmcnt(0)
	v_mfma_f32_32x32x16_bf16 v[34:49], v[120:123], v[86:89], v[34:49]
	s_nop 9
	v_max_f32_e32 v109, v51, v51
	v_max_f32_e32 v110, v52, v52
	v_max_f32_e32 v111, v53, v53
	v_max_f32_e32 v108, v35, v35
	v_max_f32_e32 v108, v109, v108
	v_max_f32_e32 v109, v36, v36
	v_max_f32_e32 v109, v110, v109
	v_max_f32_e32 v110, v37, v37
	v_max3_f32 v108, v50, v34, v108
	v_max_f32_e32 v110, v111, v110
	v_max3_f32 v108, v108, v109, v110
	v_max_f32_e32 v109, v38, v38
	v_max_f32_e32 v110, v54, v54
	v_max_f32_e32 v109, v110, v109
	v_max_f32_e32 v110, v39, v39
	v_max_f32_e32 v111, v55, v55
	v_max_f32_e32 v110, v111, v110
	v_max3_f32 v108, v108, v109, v110
	v_max_f32_e32 v109, v40, v40
	v_max_f32_e32 v110, v56, v56
	v_max_f32_e32 v109, v110, v109
	v_max_f32_e32 v110, v41, v41
	v_max_f32_e32 v111, v57, v57
	v_max_f32_e32 v110, v111, v110
	v_max3_f32 v108, v108, v109, v110
	v_max_f32_e32 v109, v42, v42
	v_max_f32_e32 v110, v58, v58
	v_max_f32_e32 v109, v110, v109
	v_max_f32_e32 v110, v43, v43
	v_max_f32_e32 v111, v59, v59
	v_max_f32_e32 v110, v111, v110
	v_max3_f32 v108, v108, v109, v110
	v_max_f32_e32 v109, v44, v44
	v_max_f32_e32 v110, v60, v60
	v_max_f32_e32 v109, v110, v109
	v_max_f32_e32 v110, v45, v45
	v_max_f32_e32 v111, v61, v61
	v_max_f32_e32 v110, v111, v110
	v_max3_f32 v108, v108, v109, v110
	v_max_f32_e32 v109, v46, v46
	v_max_f32_e32 v110, v62, v62
	v_max_f32_e32 v109, v110, v109
	v_max_f32_e32 v110, v47, v47
	v_max_f32_e32 v111, v63, v63
	v_max_f32_e32 v110, v111, v110
	v_max3_f32 v108, v108, v109, v110
	v_max_f32_e32 v109, v48, v48
	v_max_f32_e32 v110, v64, v64
	v_max_f32_e32 v109, v110, v109
	v_max_f32_e32 v110, v49, v49
	v_max_f32_e32 v111, v65, v65
	v_max_f32_e32 v110, v111, v110
	v_max3_f32 v108, v108, v109, v110
	ds_bpermute_b32 v109, v206, v108
	s_waitcnt lgkmcnt(0)
	v_max3_f32 v155, v152, v108, v109
	v_sub_f32_e32 v34, v34, v155
	v_exp_f32_e32 v110, v34
	v_sub_f32_e32 v34, v51, v155
	v_exp_f32_e32 v111, v34
	v_sub_f32_e32 v34, v35, v155
	v_exp_f32_e32 v112, v34
	v_sub_f32_e32 v34, v52, v155
	v_exp_f32_e32 v113, v34
	v_sub_f32_e32 v34, v36, v155
	v_exp_f32_e32 v114, v34
	v_sub_f32_e32 v34, v53, v155
	v_exp_f32_e32 v115, v34
	v_sub_f32_e32 v34, v37, v155
	v_exp_f32_e32 v116, v34
	v_sub_f32_e32 v34, v54, v155
	v_exp_f32_e32 v117, v34
	v_sub_f32_e32 v34, v38, v155
	v_exp_f32_e32 v118, v34
	v_sub_f32_e32 v34, v55, v155
	v_exp_f32_e32 v119, v34
	v_sub_f32_e32 v34, v39, v155
	v_exp_f32_e32 v120, v34
	v_sub_f32_e32 v34, v56, v155
	v_exp_f32_e32 v121, v34
	v_sub_f32_e32 v34, v40, v155
	v_exp_f32_e32 v122, v34
	v_sub_f32_e32 v34, v57, v155
	v_exp_f32_e32 v123, v34
	v_sub_f32_e32 v34, v41, v155
	v_exp_f32_e32 v124, v34
	v_sub_f32_e32 v34, v58, v155
	v_exp_f32_e32 v125, v34
	v_sub_f32_e32 v34, v42, v155
	v_exp_f32_e32 v126, v34
	v_sub_f32_e32 v34, v59, v155
	v_exp_f32_e32 v127, v34
	v_sub_f32_e32 v34, v43, v155
	v_exp_f32_e32 v128, v34
	v_sub_f32_e32 v34, v60, v155
	v_exp_f32_e32 v129, v34
	v_sub_f32_e32 v34, v44, v155
	v_exp_f32_e32 v134, v34
	v_sub_f32_e32 v34, v61, v155
	v_exp_f32_e32 v135, v34
	v_sub_f32_e32 v34, v45, v155
	v_exp_f32_e32 v136, v34
	v_sub_f32_e32 v34, v62, v155
	v_exp_f32_e32 v137, v34
	v_sub_f32_e32 v34, v46, v155
	v_exp_f32_e32 v138, v34
	v_sub_f32_e32 v34, v63, v155
	v_sub_f32_e32 v108, v152, v155
	v_sub_f32_e32 v50, v50, v155
	v_exp_f32_e32 v139, v34
	v_sub_f32_e32 v34, v47, v155
	v_exp_f32_e32 v109, v50
	v_exp_f32_e32 v140, v34
	v_sub_f32_e32 v34, v64, v155
	v_exp_f32_e32 v108, v108
	v_exp_f32_e32 v141, v34
	v_sub_f32_e32 v34, v48, v155
	ds_read_b128 v[38:41], v153 offset:26624
	ds_read_b128 v[42:45], v153 offset:26656
	v_exp_f32_e32 v142, v34
	v_sub_f32_e32 v34, v65, v155
	v_exp_f32_e32 v143, v34
	v_sub_f32_e32 v34, v49, v155
	v_exp_f32_e32 v144, v34
	v_pk_mul_f32 v[32:33], v[32:33], v[108:109] op_sel_hi:[1,0]
	v_pk_mul_f32 v[30:31], v[30:31], v[108:109] op_sel_hi:[1,0]
	v_pk_mul_f32 v[28:29], v[28:29], v[108:109] op_sel_hi:[1,0]
	v_pk_mul_f32 v[26:27], v[26:27], v[108:109] op_sel_hi:[1,0]
	v_pk_mul_f32 v[24:25], v[24:25], v[108:109] op_sel_hi:[1,0]
	v_pk_mul_f32 v[22:23], v[22:23], v[108:109] op_sel_hi:[1,0]
	v_pk_mul_f32 v[20:21], v[20:21], v[108:109] op_sel_hi:[1,0]
	v_pk_mul_f32 v[18:19], v[18:19], v[108:109] op_sel_hi:[1,0]
	v_cvt_pk_bf16_f32 v34, v109, v111
	v_cvt_pk_bf16_f32 v35, v113, v115
	v_cvt_pk_bf16_f32 v36, v117, v119
	v_cvt_pk_bf16_f32 v37, v121, v123
	v_pk_mul_f32 v[16:17], v[16:17], v[108:109] op_sel_hi:[1,0]
	v_pk_mul_f32 v[14:15], v[14:15], v[108:109] op_sel_hi:[1,0]
	s_waitcnt lgkmcnt(1)
; #define MFMA(a, b, c) __builtin_amdgcn_mfma_f32_32x32x16_bf16((a), (b), (c), 0, 0, 0)
; template <int NCH, int MODE, bool BOUND> ...
;     ...
;     const char* kb0 = cur + (hf * 64 + r) * KSTR + h * 16;
;     constexpr int NC2 = NCH < 2 ? NCH : 2;
;     bf16x8 ka[NC2][2], kb[NC2][2], kc[2], kd[2];
; #pragma unroll
;     for (int c = 0; c < NC2; ++c)
; #pragma unroll
;       for (int ks = 0; ks < 2; ++ks) {
;         ka[c][ks] = *(const bf16x8*)(kb0 + c * 64 + ks * 32);
;         kb[c][ks] = *(const bf16x8*)(kb0 + 32 * KSTR + c * 64 + ks * 32);
;       }
;     __builtin_amdgcn_sched_barrier(0);
;     if (NCH == 3) {
; #pragma unroll
;       for (int ks = 0; ks < 2; ++ks) {
;         kc[ks] = *(const bf16x8*)(kb0 + 2 * 64 + ks * 32);
;         kd[ks] = *(const bf16x8*)(kb0 + 32 * KSTR + 2 * 64 + ks * 32);
;       }
;     }
; #pragma unroll
;     for (int c = 0; c < NC2; ++c)
; #pragma unroll
;       for (int ks = 0; ks < 2; ++ks) {
;         s0 = MFMA(ka[c][ks], qf[c][ks], s0);
;         s1 = MFMA(kb[c][ks], qf[c][ks], s1);
;       }
;     if (NCH == 3) {
; #pragma unroll
;       for (int ks = 0; ks < 2; ++ks) {
;         s0 = MFMA(kc[ks], qf[NCH - 1][ks], s0);
;         s1 = MFMA(kd[ks], qf[NCH - 1][ks], s1);
;       }
;     }
;     ...
;     const char* vb0 = cur + A_VOFF + r * V_ROW + hf * 128 + 16 * h;
; #pragma unroll
;     for (int kb = 0; kb < 2; ++kb)
; #pragma unroll
;       for (int s = 0; s < 2; ++s) {
;         uint4 pu;
;         if (kb == 0) {
;           pu.x = pk_bf16(s0[8 * s + 0], s0[8 * s + 1]); pu.y = pk_bf16(s0[8 * s + 2], s0[8 * s + 3]);
;           pu.z = pk_bf16(s0[8 * s + 4], s0[8 * s + 5]); pu.w = pk_bf16(s0[8 * s + 6], s0[8 * s + 7]);
;         } else {
;           pu.x = pk_bf16(s1[8 * s + 0], s1[8 * s + 1]); pu.y = pk_bf16(s1[8 * s + 2], s1[8 * s + 3]);
;           pu.z = pk_bf16(s1[8 * s + 4], s1[8 * s + 5]); pu.w = pk_bf16(s1[8 * s + 6], s1[8 * s + 7]);
;         }
;         const bf16x8 pf = __builtin_bit_cast(bf16x8, pu);
;         const int koff = (kb * 32 + 16 * s) * 2;
;         {
;           const bf16x8 vf = *(const bf16x8*)(vb0 + koff);
;           o0 = MFMA(vf, pf, o0);
;         }
;         {
;           const bf16x8 vf = *(const bf16x8*)(vb0 + 32 * V_ROW + koff);
;           o1 = MFMA(vf, pf, o1);
;         }
;       }
	v_mfma_f32_32x32x16_bf16 v[18:33], v[38:41], v[34:37], v[18:33]
	ds_read_b128 v[38:41], v153 offset:35328
	v_mul_f32_e64 v12, v12, v108
	v_mul_f32_e64 v13, v13, v108
	v_mul_f32_e64 v10, v10, v108
	v_mul_f32_e64 v11, v11, v108
	v_pk_mul_f32 v[8:9], v[8:9], v[108:109] op_sel_hi:[1,0]
	v_pk_mul_f32 v[6:7], v[6:7], v[108:109] op_sel_hi:[1,0]
	v_pk_mul_f32 v[4:5], v[4:5], v[108:109] op_sel_hi:[1,0]
	v_pk_mul_f32 v[2:3], v[2:3], v[108:109] op_sel_hi:[1,0]
	s_waitcnt lgkmcnt(0)
	s_nop 0
	v_mfma_f32_32x32x16_bf16 v[2:17], v[38:41], v[34:37], v[2:17]
	ds_read_b128 v[38:41], v153 offset:35360
	v_cvt_pk_bf16_f32 v34, v125, v127
	v_cvt_pk_bf16_f32 v35, v129, v135
	v_cvt_pk_bf16_f32 v36, v137, v139
	v_cvt_pk_bf16_f32 v37, v141, v143
	s_waitcnt lgkmcnt(0)
	s_nop 0
	v_mfma_f32_32x32x16_bf16 v[2:17], v[38:41], v[34:37], v[2:17]
	ds_read_b128 v[38:41], v153 offset:26688
	v_mfma_f32_32x32x16_bf16 v[18:33], v[42:45], v[34:37], v[18:33]
	v_cvt_pk_bf16_f32 v34, v110, v112
	v_cvt_pk_bf16_f32 v35, v114, v116
	v_cvt_pk_bf16_f32 v36, v118, v120
	v_cvt_pk_bf16_f32 v37, v122, v124
	s_waitcnt lgkmcnt(0)
	s_nop 0
	v_mfma_f32_32x32x16_bf16 v[18:33], v[38:41], v[34:37], v[18:33]
	ds_read_b128 v[38:41], v153 offset:35392
	s_waitcnt lgkmcnt(0)
	v_mfma_f32_32x32x16_bf16 v[2:17], v[38:41], v[34:37], v[2:17]
	ds_read_b128 v[38:41], v153 offset:26720
	v_cvt_pk_bf16_f32 v34, v126, v128
	v_cvt_pk_bf16_f32 v35, v134, v136
	v_cvt_pk_bf16_f32 v36, v138, v140
	v_cvt_pk_bf16_f32 v37, v142, v144
	s_waitcnt lgkmcnt(0)
	s_nop 0
	v_mfma_f32_32x32x16_bf16 v[18:33], v[38:41], v[34:37], v[18:33]
	ds_read_b128 v[38:41], v153 offset:35424
	s_waitcnt lgkmcnt(0)
	v_mfma_f32_32x32x16_bf16 v[2:17], v[38:41], v[34:37], v[2:17]
	ds_read_b128 v[34:37], v154 offset:13824
	ds_read_b128 v[38:41], v154 offset:9216
	ds_read_b128 v[156:159], v154 offset:9248
	ds_read_b128 v[160:163], v154 offset:13856
	ds_read_b128 v[168:171], v154 offset:9280
	ds_read_b128 v[172:175], v154 offset:13888
	ds_read_b128 v[176:179], v154 offset:9312
	ds_read_b128 v[180:183], v154 offset:13920
	s_waitcnt lgkmcnt(6)
	v_mfma_f32_32x32x16_bf16 v[50:65], v[38:41], v[74:77], 0
	s_andn2_b64 vcc, exec, s[44:45]
	v_mfma_f32_32x32x16_bf16 v[34:49], v[34:37], v[74:77], 0
	s_waitcnt lgkmcnt(5)
	v_mfma_f32_32x32x16_bf16 v[50:65], v[156:159], v[78:81], v[50:65]
	s_waitcnt lgkmcnt(4)
	v_mfma_f32_32x32x16_bf16 v[34:49], v[160:163], v[78:81], v[34:49]
	s_waitcnt lgkmcnt(3)
	v_mfma_f32_32x32x16_bf16 v[50:65], v[168:171], v[82:85], v[50:65]
	ds_read_b128 v[160:163], v153 offset:26752
	ds_read_b128 v[168:171], v153 offset:26784
	s_waitcnt lgkmcnt(4)
	v_mfma_f32_32x32x16_bf16 v[34:49], v[172:175], v[82:85], v[34:49]
	s_waitcnt lgkmcnt(3)
	v_mfma_f32_32x32x16_bf16 v[50:65], v[176:179], v[86:89], v[50:65]
	s_waitcnt lgkmcnt(2)
	v_mfma_f32_32x32x16_bf16 v[34:49], v[180:183], v[86:89], v[34:49]
	s_nop 9
	v_max_f32_e32 v154, v51, v51
	v_max_f32_e32 v156, v52, v52
	v_max_f32_e32 v157, v53, v53
	v_max_f32_e32 v152, v35, v35
	v_max_f32_e32 v152, v154, v152
	v_max_f32_e32 v154, v36, v36
	v_max_f32_e32 v154, v156, v154
	v_max_f32_e32 v156, v37, v37
	v_max3_f32 v152, v50, v34, v152
	v_max_f32_e32 v156, v157, v156
	v_max3_f32 v152, v152, v154, v156
	v_max_f32_e32 v154, v38, v38
	v_max_f32_e32 v156, v54, v54
	v_max_f32_e32 v154, v156, v154
	v_max_f32_e32 v156, v39, v39
	v_max_f32_e32 v157, v55, v55
	v_max_f32_e32 v156, v157, v156
	v_max3_f32 v152, v152, v154, v156
	v_max_f32_e32 v154, v40, v40
	v_max_f32_e32 v156, v56, v56
	v_max_f32_e32 v154, v156, v154
	v_max_f32_e32 v156, v41, v41
	v_max_f32_e32 v157, v57, v57
	v_max_f32_e32 v156, v157, v156
	v_max3_f32 v152, v152, v154, v156
	v_max_f32_e32 v154, v42, v42
	v_max_f32_e32 v156, v58, v58
	v_max_f32_e32 v154, v156, v154
	v_max_f32_e32 v156, v43, v43
	v_max_f32_e32 v157, v59, v59
	v_max_f32_e32 v156, v157, v156
	v_max3_f32 v152, v152, v154, v156
	v_max_f32_e32 v154, v44, v44
	v_max_f32_e32 v156, v60, v60
	v_max_f32_e32 v154, v156, v154
	v_max_f32_e32 v156, v45, v45
	v_max_f32_e32 v157, v61, v61
	v_max_f32_e32 v156, v157, v156
	v_max3_f32 v152, v152, v154, v156
	v_max_f32_e32 v154, v46, v46
	v_max_f32_e32 v156, v62, v62
	v_max_f32_e32 v154, v156, v154
	v_max_f32_e32 v156, v47, v47
	v_max_f32_e32 v157, v63, v63
	v_max_f32_e32 v156, v157, v156
	v_max3_f32 v152, v152, v154, v156
	v_max_f32_e32 v154, v48, v48
	v_max_f32_e32 v156, v64, v64
	v_max_f32_e32 v154, v156, v154
	v_max_f32_e32 v156, v49, v49
	v_max_f32_e32 v157, v65, v65
	v_max_f32_e32 v156, v157, v156
	v_max3_f32 v152, v152, v154, v156
	ds_bpermute_b32 v154, v206, v152
	s_waitcnt lgkmcnt(0)
; #define MFMA(a, b, c) __builtin_amdgcn_mfma_f32_32x32x16_bf16((a), (b), (c), 0, 0, 0)
; DI float fexp2(float x) { return __builtin_amdgcn_exp2f(x); }
; DI float xhalf(float v) { return __shfl_xor(v, 32); }
; template <int NCH, int MODE, bool BOUND> ...
;     ...
;       float mx = fmaxf(s0[0], s1[0]);
; #pragma unroll
;       for (int i = 1; i < 16; ++i) mx = fmaxf(mx, fmaxf(s0[i], s1[i]));
;       mx = fmaxf(mx, xhalf(mx));
;       const float mnew = fmaxf(m, mx);
;       const float alpha = fexp2(m - mnew);
;       m = mnew;
;       float ps = 0.f;
; #pragma unroll
;       for (int i = 0; i < 16; ++i) {
;         s0[i] = fexp2(s0[i] - mnew);
;         s1[i] = fexp2(s1[i] - mnew);
;         ps += s0[i] + s1[i];
;       }
;       l = l * alpha + ps;
; #pragma unroll
;       for (int i = 0; i < 16; ++i) { o0[i] *= alpha; o1[i] *= alpha; }
;     }
;     const char* vb0 = cur + A_VOFF + r * V_ROW + hf * 128 + 16 * h;
; #pragma unroll
;     for (int kb = 0; kb < 2; ++kb)
; #pragma unroll
;       for (int s = 0; s < 2; ++s) {
;         uint4 pu;
;         if (kb == 0) {
;           pu.x = pk_bf16(s0[8 * s + 0], s0[8 * s + 1]); pu.y = pk_bf16(s0[8 * s + 2], s0[8 * s + 3]);
;           pu.z = pk_bf16(s0[8 * s + 4], s0[8 * s + 5]); pu.w = pk_bf16(s0[8 * s + 6], s0[8 * s + 7]);
;         } else {
;           pu.x = pk_bf16(s1[8 * s + 0], s1[8 * s + 1]); pu.y = pk_bf16(s1[8 * s + 2], s1[8 * s + 3]);
;           pu.z = pk_bf16(s1[8 * s + 4], s1[8 * s + 5]); pu.w = pk_bf16(s1[8 * s + 6], s1[8 * s + 7]);
;         }
;         const bf16x8 pf = __builtin_bit_cast(bf16x8, pu);
;         const int koff = (kb * 32 + 16 * s) * 2;
;         {
;           const bf16x8 vf = *(const bf16x8*)(vb0 + koff);
;           o0 = MFMA(vf, pf, o0);
;         }
;         {
;           const bf16x8 vf = *(const bf16x8*)(vb0 + 32 * V_ROW + koff);
;           o1 = MFMA(vf, pf, o1);
;         }
;       }
;     ...
;     if (more) lstore(smem + ((t - t0 + 1) & 1) * A_STAGE);
;     __syncthreads();
;   }
	v_max3_f32 v152, v155, v152, v154
	v_sub_f32_e32 v34, v34, v152
	v_exp_f32_e32 v154, v34
	v_sub_f32_e32 v34, v51, v152
	v_exp_f32_e32 v51, v34
	v_sub_f32_e32 v34, v35, v152
	v_exp_f32_e32 v35, v34
	v_sub_f32_e32 v34, v52, v152
	v_exp_f32_e32 v52, v34
	v_sub_f32_e32 v34, v36, v152
	v_exp_f32_e32 v36, v34
	v_sub_f32_e32 v34, v53, v152
	v_exp_f32_e32 v53, v34
	v_sub_f32_e32 v34, v37, v152
	v_exp_f32_e32 v37, v34
	v_sub_f32_e32 v34, v54, v152
	v_exp_f32_e32 v54, v34
	v_sub_f32_e32 v34, v38, v152
	v_exp_f32_e32 v38, v34
	v_sub_f32_e32 v34, v55, v152
	v_exp_f32_e32 v55, v34
	v_sub_f32_e32 v34, v39, v152
	v_exp_f32_e32 v39, v34
	v_sub_f32_e32 v34, v56, v152
	v_exp_f32_e32 v56, v34
	v_sub_f32_e32 v34, v40, v152
	v_exp_f32_e32 v40, v34
	v_sub_f32_e32 v34, v57, v152
	v_exp_f32_e32 v57, v34
	v_sub_f32_e32 v34, v41, v152
	v_exp_f32_e32 v41, v34
	v_sub_f32_e32 v34, v58, v152
	v_exp_f32_e32 v58, v34
	v_sub_f32_e32 v34, v42, v152
	v_exp_f32_e32 v42, v34
	v_sub_f32_e32 v34, v59, v152
	v_exp_f32_e32 v59, v34
	v_sub_f32_e32 v34, v43, v152
	v_exp_f32_e32 v43, v34
	v_sub_f32_e32 v34, v60, v152
	v_exp_f32_e32 v60, v34
	v_sub_f32_e32 v34, v44, v152
	v_exp_f32_e32 v44, v34
	v_sub_f32_e32 v34, v61, v152
	v_exp_f32_e32 v61, v34
	v_sub_f32_e32 v34, v45, v152
	v_exp_f32_e32 v45, v34
	v_sub_f32_e32 v34, v62, v152
	v_exp_f32_e32 v62, v34
	v_sub_f32_e32 v34, v46, v152
	v_exp_f32_e32 v46, v34
	v_sub_f32_e32 v34, v63, v152
	v_exp_f32_e32 v63, v34
	v_sub_f32_e32 v34, v47, v152
	v_exp_f32_e32 v47, v34
	v_sub_f32_e32 v34, v64, v152
	v_exp_f32_e32 v64, v34
	v_sub_f32_e32 v34, v48, v152
	v_exp_f32_e32 v48, v34
	v_sub_f32_e32 v34, v65, v152
	v_sub_f32_e32 v155, v155, v152
	v_sub_f32_e32 v50, v50, v152
	v_exp_f32_e32 v65, v34
	v_sub_f32_e32 v34, v49, v152
	v_exp_f32_e32 v50, v50
	v_exp_f32_e32 v49, v34
	v_exp_f32_e32 v34, v155
	v_cvt_pk_bf16_f32 v157, v52, v53
	v_cvt_pk_bf16_f32 v156, v50, v51
	v_cvt_pk_bf16_f32 v158, v54, v55
	v_pk_mul_f32 v[32:33], v[32:33], v[34:35] op_sel_hi:[1,0]
	v_pk_mul_f32 v[30:31], v[30:31], v[34:35] op_sel_hi:[1,0]
	v_pk_mul_f32 v[28:29], v[28:29], v[34:35] op_sel_hi:[1,0]
	v_pk_mul_f32 v[26:27], v[26:27], v[34:35] op_sel_hi:[1,0]
	v_pk_mul_f32 v[24:25], v[24:25], v[34:35] op_sel_hi:[1,0]
	v_pk_mul_f32 v[22:23], v[22:23], v[34:35] op_sel_hi:[1,0]
	v_pk_mul_f32 v[20:21], v[20:21], v[34:35] op_sel_hi:[1,0]
	v_pk_mul_f32 v[18:19], v[18:19], v[34:35] op_sel_hi:[1,0]
	v_cvt_pk_bf16_f32 v159, v56, v57
	v_pk_mul_f32 v[16:17], v[16:17], v[34:35] op_sel_hi:[1,0]
	v_pk_mul_f32 v[14:15], v[14:15], v[34:35] op_sel_hi:[1,0]
	v_mfma_f32_32x32x16_bf16 v[18:33], v[160:163], v[156:159], v[18:33]
	ds_read_b128 v[160:163], v153 offset:35456
	v_mul_f32_e64 v12, v12, v34
	v_mul_f32_e64 v13, v13, v34
	v_mul_f32_e64 v10, v10, v34
	v_mul_f32_e64 v11, v11, v34
	v_pk_mul_f32 v[8:9], v[8:9], v[34:35] op_sel_hi:[1,0]
	v_pk_mul_f32 v[6:7], v[6:7], v[34:35] op_sel_hi:[1,0]
	v_pk_mul_f32 v[4:5], v[4:5], v[34:35] op_sel_hi:[1,0]
	v_pk_mul_f32 v[2:3], v[2:3], v[34:35] op_sel_hi:[1,0]
	s_waitcnt lgkmcnt(0)
	s_nop 0
	v_mfma_f32_32x32x16_bf16 v[2:17], v[160:163], v[156:159], v[2:17]
	ds_read_b128 v[160:163], v153 offset:35488
	v_cvt_pk_bf16_f32 v156, v58, v59
	v_cvt_pk_bf16_f32 v157, v60, v61
	v_cvt_pk_bf16_f32 v158, v62, v63
	v_cvt_pk_bf16_f32 v159, v64, v65
	s_waitcnt lgkmcnt(0)
	s_nop 0
	v_mfma_f32_32x32x16_bf16 v[2:17], v[160:163], v[156:159], v[2:17]
	ds_read_b128 v[160:163], v153 offset:26816
	v_mfma_f32_32x32x16_bf16 v[18:33], v[168:171], v[156:159], v[18:33]
	v_cvt_pk_bf16_f32 v156, v154, v35
	v_cvt_pk_bf16_f32 v157, v36, v37
	v_cvt_pk_bf16_f32 v158, v38, v39
	v_cvt_pk_bf16_f32 v159, v40, v41
	s_waitcnt lgkmcnt(0)
	s_nop 0
	v_mfma_f32_32x32x16_bf16 v[18:33], v[160:163], v[156:159], v[18:33]
	ds_read_b128 v[160:163], v153 offset:35520
	s_waitcnt lgkmcnt(0)
	v_mfma_f32_32x32x16_bf16 v[2:17], v[160:163], v[156:159], v[2:17]
	ds_read_b128 v[160:163], v153 offset:26848
	v_cvt_pk_bf16_f32 v156, v42, v43
	v_cvt_pk_bf16_f32 v157, v44, v45
	v_cvt_pk_bf16_f32 v158, v46, v47
	v_cvt_pk_bf16_f32 v159, v48, v49
	s_waitcnt lgkmcnt(0)
	s_nop 0
	v_mfma_f32_32x32x16_bf16 v[18:33], v[160:163], v[156:159], v[18:33]
	ds_read_b128 v[160:163], v153 offset:35552
	s_waitcnt lgkmcnt(0)
	v_mfma_f32_32x32x16_bf16 v[2:17], v[160:163], v[156:159], v[2:17]
	s_cbranch_vccnz .LBB0_318
	s_andn2_b32 s8, 1, s50
	s_mul_i32 s8, s8, 0xac00
	s_add_i32 s8, s8, 0
	v_add_u32_e32 v155, s8, v98
	v_add_u32_e32 v153, s8, v104
	s_waitcnt vmcnt(3)
	ds_write_b128 v155, v[66:69]
	s_waitcnt vmcnt(2)
	ds_write_b128 v155, v[70:73] offset:64
	s_waitcnt vmcnt(1)
	ds_write_b128 v153, v[90:93] offset:26624
	s_waitcnt vmcnt(0)
	ds_write_b128 v153, v[94:97] offset:35328
	s_branch .LBB0_318
; DI int otid() { int t = threadIdx.x; asm volatile("" : "+v"(t)); return t; }
; template <int NCH, int MODE, bool BOUND> ...
;     ...
;   const int tid = otid(), lane = tid & 63, r = lane & 31, h = lane >> 5;
;   bf16x8 qf[NCH][2];
; #pragma unroll
;   for (int c = 0; c < NCH; ++c) {
;     const bf16_t* qp = (c == 0) ? q0p : (c == 1) ? q1p : q2p;
; #pragma unroll
;     for (int ks = 0; ks < 2; ++ks) qf[c][ks] = *(const bf16x8*)(qp + (size_t)qtok * 64 + ks * 16 + 8 * h);
;   }
;   const int krow = tid >> 2, kseg = tid & 3;
;   const size_t koff_g = ((size_t)b * SEQ + krow) * 64 + kseg * 8;
;   const int kdst = krow * KSTR + kseg * 16;
;   const int vd = tid >> 4, vseg = tid & 15;
;   const bf16_t* vsrc = vt + ((size_t)b * 64 + vd) * SEQ + vseg * 8;
;   const int vdst = A_VOFF + vd * V_ROW + vseg * 16;
;   uint4 kr0, kr1, kr2, vr0, vr1;
;   auto gload_k = [&](int t) {
;     kr0 = *(const uint4*)(k0p + koff_g + (size_t)t * 128 * 64);
;     if (NCH > 1) kr1 = *(const uint4*)(k1p + koff_g + (size_t)t * 128 * 64);
;     if (NCH > 2) kr2 = *(const uint4*)(k2p + koff_g + (size_t)t * 128 * 64);
;   };
;   auto gload_v = [&](int t) {
;     vr0 = *(const uint4*)(vsrc + t * 128);
;     vr1 = *(const uint4*)(vsrc + (size_t)32 * SEQ + t * 128);
;   };
;   auto lstore = [&](char* st) {
;     *(uint4*)(st + kdst) = kr0;
;     if (NCH > 1) *(uint4*)(st + kdst + 64) = kr1;
;     if (NCH > 2) *(uint4*)(st + kdst + 128) = kr2;
;     *(uint4*)(st + vdst) = vr0;
;     *(uint4*)(st + vdst + 32 * V_ROW) = vr1;
;   };
;   kr1 = make_uint4(0, 0, 0, 0); kr2 = kr1;
;   gload_k(t0); gload_v(t0);
;   lstore(smem);
;   __syncthreads();
; #pragma unroll
;   for (int c = 0; c < NCH; ++c)
; #pragma unroll
;     for (int ks = 0; ks < 2; ++ks) asm volatile("" : "+v"(qf[c][ks]));
;   float m = -1e30f, l = 0.f;
; #pragma unroll
;   for (int i = 0; i < 16; ++i) { o0[i] = 0.f; o1[i] = 0.f; }
.Lhop_to_9:
	s_branch .LBB0_9
.LBB0_323:
	v_mov_b32_e32 v47, v228
	v_mov_b32_e32 v51, v1
	v_ashrrev_i32_e32 v44, 2, v47
	v_ashrrev_i32_e32 v45, 31, v44
	v_lshlrev_b64 v[34:35], 6, v[44:45]
	v_ashrrev_i32_e32 v48, 4, v47
	v_and_b32_e32 v36, 3, v47
	v_lshl_add_u64 v[34:35], v[34:35], 0, s[4:5]
	v_ashrrev_i32_e32 v49, 31, v48
	v_lshl_or_b32 v34, v36, 3, v34
	v_lshlrev_b32_e32 v46, 4, v36
	v_lshlrev_b64 v[36:37], 13, v[48:49]
	v_lshlrev_b32_e32 v38, 4, v47
	v_mad_u64_u32 v[134:135], s[8:9], v44, s33, v[46:47]
	v_lshl_add_u64 v[36:37], s[40:41], 0, v[36:37]
	v_and_b32_e32 v50, 0xf0, v38
	v_lshl_add_u64 v[136:137], v[36:37], 0, v[50:51]
	s_mov_b64 s[8:9], 0x40000
	v_lshlrev_b64 v[34:35], 1, v[34:35]
	v_lshl_add_u64 v[138:139], v[136:137], 0, s[8:9]
	s_mov_b32 s8, 0x40000
	v_lshl_add_u64 v[36:37], s[0:1], 0, v[34:35]
	v_lshl_add_u64 v[34:35], s[2:3], 0, v[34:35]
	v_add_co_u32_e32 v38, vcc, s8, v136
	global_load_dwordx4 v[98:101], v[36:37], off
	global_load_dwordx4 v[102:105], v[34:35], off
	s_nop 0
	global_load_dwordx4 v[34:37], v[136:137], off
	v_addc_co_u32_e32 v39, vcc, 0, v137, vcc
	global_load_dwordx4 v[38:41], v[38:39], off
	s_movk_i32 s8, 0x110
	v_lshrrev_b32_e32 v0, 1, v47
	v_mad_u64_u32 v[140:141], s[8:9], v48, s8, v[50:51]
	v_and_b32_e32 v0, 16, v0
	v_add_u32_e32 v49, 0, v134
	v_add_u32_e32 v48, 0, v140
	v_lshl_add_u64 v[42:43], v[132:133], 0, v[0:1]
	ds_bpermute_b32 v152, v206, v145
	v_mov_b32_e32 v153, 0
	s_mov_b32 s11, 0
	v_mov_b32_e32 v188, 0xf149f2ca
	s_mov_b64 s[30:31], 0x80
	v_mov_b32_e32 v50, 0
	v_mov_b32_e32 v51, v153
	v_mov_b32_e32 v52, v153
	v_mov_b32_e32 v53, v153
	v_mov_b32_e32 v54, v153
	v_mov_b32_e32 v55, v153
	v_mov_b32_e32 v56, v153
	v_mov_b32_e32 v57, v153
	v_mov_b32_e32 v58, v153
	v_mov_b32_e32 v59, v153
	v_mov_b32_e32 v60, v153
	v_mov_b32_e32 v61, v153
	v_mov_b32_e32 v62, v153
	v_mov_b32_e32 v63, v153
	v_mov_b32_e32 v64, v153
	v_mov_b32_e32 v65, v153
	s_movk_i32 s43, 0xff
	s_waitcnt vmcnt(3)
	ds_write_b128 v49, v[98:101]
	s_waitcnt vmcnt(2)
	ds_write_b128 v49, v[102:105] offset:64
	s_waitcnt vmcnt(1)
	ds_write_b128 v48, v[34:37] offset:26624
	s_waitcnt vmcnt(0)
	ds_write_b128 v48, v[38:41] offset:35328
	global_load_dwordx4 v[106:109], v[42:43], off
	global_load_dwordx4 v[110:113], v[42:43], off offset:32
	global_load_dwordx4 v[114:117], v[42:43], off offset:64
	global_load_dwordx4 v[118:121], v[42:43], off offset:96
	v_and_b32_e32 v34, 31, v47
	v_mul_u32_u24_e32 v135, 0x90, v34
	v_mul_u32_u24_e32 v141, 0x110, v34
	v_lshlrev_b64 v[34:35], 7, v[44:45]
	v_lshl_add_u64 v[34:35], s[28:29], 0, v[34:35]
	v_mov_b32_e32 v47, v1
	v_lshl_add_u64 v[34:35], v[34:35], 0, v[46:47]
	v_lshl_add_u64 v[142:143], s[6:7], 0, v[34:35]
	s_mov_b64 s[28:29], 0
	v_mov_b32_e32 v34, 0
	v_mov_b32_e32 v35, v153
	v_mov_b32_e32 v36, v153
	v_mov_b32_e32 v37, v153
	v_mov_b32_e32 v38, v153
	v_mov_b32_e32 v39, v153
	v_mov_b32_e32 v40, v153
	v_mov_b32_e32 v41, v153
	v_mov_b32_e32 v42, v153
	v_mov_b32_e32 v43, v153
	v_mov_b32_e32 v44, v153
	v_mov_b32_e32 v45, v153
	v_mov_b32_e32 v46, v153
	v_mov_b32_e32 v47, v153
	v_mov_b32_e32 v48, v153
	v_mov_b32_e32 v49, v153
	s_waitcnt lgkmcnt(0)
	s_barrier
	s_waitcnt vmcnt(3)
	s_waitcnt vmcnt(2)
	s_waitcnt vmcnt(1)
	s_waitcnt vmcnt(0)
	s_branch .LBB0_325
